# end-of-M barrier issued before the last 1-2 MFMAs with a priority ladder (M at prio 2, tail at prio 3) so the next wave's MFMAs start without a handoff bubble
# speedup vs baseline: 1.0103x; 1.0103x over previous
; #define PG8_STAGE(bufoff, gbase, voff) do { _Pragma("unroll") for (int _i = 0; _i < 2; ++_i) \
;         __builtin_amdgcn_global_load_lds((const unsigned*)((const char*)(gbase) + (voff)[_i]), (LAS unsigned*)(lds + (bufoff) + ldsw + _i * 8192), 16, 0, 0); } while (0)
; #define PG8_LDA(dst, b, h) do { _Pragma("unroll") for (int m = 0; m < 4; ++m) _Pragma("unroll") for (int k = 0; k < 2; ++k) dst[m][k] = *(const LAS bf16x8*)(lds + PG8_SA(b, h) + aoff + m * 2048 + k * 1024); } while (0)
; #define PG8_LDB(dst, b, h) do { _Pragma("unroll") for (int n = 0; n < 2; ++n) _Pragma("unroll") for (int k = 0; k < 2; ++k) dst[n][k] = *(const LAS bf16x8*)(lds + PG8_SB(b, h) + boff + n * 2048 + k * 1024); } while (0)
; #define PG8_MMA(ai, bj, At, Bt) do { __builtin_amdgcn_s_setprio(3); _Pragma("unroll") for (int m = 0; m < 4; ++m) _Pragma("unroll") for (int n = 0; n < 2; ++n) _Pragma("unroll") for (int k = 0; k < 2; ++k) \
;         acc[ai][bj][m][n] = __builtin_amdgcn_mfma_f32_16x16x32_bf16(Bt[n][k], At[m][k], acc[ai][bj][m][n], 0, 0, 0); __builtin_amdgcn_s_setprio(0); } while (0)
; #define PG8_WAIT_V(n) asm volatile("s_waitcnt vmcnt(" #n ")" ::: "memory")
; #define PG8_WAIT_L(n) asm volatile("s_waitcnt lgkmcnt(" #n ")" ::: "memory")
; #define PG8_BAR __builtin_amdgcn_s_barrier()
; template <class Epi, class Sched, bool ALIGN_EPI = false, bool SP2 = false>
; __device__ __forceinline__ void gemm_phase(LAS unsigned char* lds, const Gemm g, const Sched& S, const Epi& E) {
;     ...
;             const char* a2 = last ? nA : cA + (size_t)(t + 2) * kstep; const char* b2 = last ? nB : cB + (size_t)(t + 2) * kstep;
;             const char* a3 = a2 + kstep; const char* b3 = b2 + kstep;
;             if (last && has_next) S.a_ready(nxt);
;             if constexpr (Epi::MID) { if (t == nt / 2) E.mid(acc, cur, wr, wc, fr, fq); }
;             if constexpr (SP2) {
;             PG8_LDB(B0, 0, 0); PG8_LDB(B1, 0, 1); PG8_SCHED; PG8_LDA(At, 0, 0); PG8_STAGE(PG8_SA(1, 1), a1 + hsA, voffA);
;             PG8_WAIT_V(8); PG8_WAIT_L(0); PG8_BAR; PG8_MMA(0, 0, At, B0); PG8_MMA(0, 1, At, B1); PG8_BAR; PG8_SCHED;
;             PG8_LDA(At, 0, 1); PG8_STAGE(PG8_SB(0, 0), b2, voffB); PG8_STAGE(PG8_SB(0, 1), b2 + hsB, voffB); PG8_STAGE(PG8_SA(0, 0), a2, voffA);
;             PG8_WAIT_V(8); PG8_WAIT_L(0); PG8_BAR; PG8_MMA(1, 0, At, B0); PG8_MMA(1, 1, At, B1); PG8_BAR; PG8_SCHED;
.LBB0_64:
	ds_read_b128 v[128:131], v158
	ds_read_b128 v[150:153], v251
	ds_read_b128 v[166:169], v158 offset:2048
	ds_read_b128 v[170:173], v251 offset:2048
	ds_read_b128 v[174:177], v159
	ds_read_b128 v[178:181], v252
	ds_read_b128 v[182:185], v159 offset:2048
	ds_read_b128 v[186:189], v252 offset:2048
	s_add_u32 s6, s4, 0xffefc080
	s_addc_u32 s7, s5, -1
	s_cmp_eq_u32 s91, 60
	s_cselect_b32 s63, s59, s7
	s_cselect_b32 s62, s58, s6
	s_cselect_b32 s7, s61, s90
	s_cselect_b32 s6, s60, s89
	s_sub_u32 s100, s4, 0x104000
	s_subb_u32 s101, s5, 0
	v_lshl_add_u64 v[242:243], s[100:101], 0, v[132:133]
	s_mov_b32 m0, s76
	v_lshl_add_u64 v[244:245], s[100:101], 0, v[136:137]
	global_load_lds_dwordx4 v[242:243], off
	s_mov_b32 m0, s77
	s_nop 0
	global_load_lds_dwordx4 v[244:245], off
	v_lshl_add_u64 v[226:227], s[4:5], 0, v[142:143]
	s_add_i32 m0, s68, 0xc000
	ds_read_b128 v[190:193], v160
	ds_read_b128 v[194:197], v250
	ds_read_b128 v[198:201], v160 offset:2048
	ds_read_b128 v[206:209], v250 offset:2048
	ds_read_b128 v[210:213], v160 offset:4096
	ds_read_b128 v[214:217], v250 offset:4096
	ds_read_b128 v[218:221], v160 offset:6144
	ds_read_b128 v[222:225], v250 offset:6144
	global_load_lds_dwordx4 v[226:227], off
	v_lshl_add_u64 v[226:227], s[4:5], 0, v[144:145]
	s_add_i32 m0, s68, 0xe000
	s_nop 0
	global_load_lds_dwordx4 v[226:227], off
	s_waitcnt vmcnt(8)
	s_waitcnt lgkmcnt(0)
	s_barrier
	s_setprio 2
	s_waitcnt lgkmcnt(0)
	v_mfma_f32_16x16x32_bf16 v[124:127], v[128:131], v[190:193], v[124:127]
	v_mfma_f32_16x16x32_bf16 v[124:127], v[150:153], v[194:197], v[124:127]
	v_mfma_f32_16x16x32_bf16 v[120:123], v[166:169], v[190:193], v[120:123]
	v_mfma_f32_16x16x32_bf16 v[120:123], v[170:173], v[194:197], v[120:123]
	v_mfma_f32_16x16x32_bf16 v[108:111], v[128:131], v[198:201], v[108:111]
	v_mfma_f32_16x16x32_bf16 v[108:111], v[150:153], v[206:209], v[108:111]
	v_mfma_f32_16x16x32_bf16 v[104:107], v[166:169], v[198:201], v[104:107]
	v_mfma_f32_16x16x32_bf16 v[104:107], v[170:173], v[206:209], v[104:107]
	v_mfma_f32_16x16x32_bf16 v[92:95], v[128:131], v[210:213], v[92:95]
	v_mfma_f32_16x16x32_bf16 v[92:95], v[150:153], v[214:217], v[92:95]
	v_mfma_f32_16x16x32_bf16 v[88:91], v[166:169], v[210:213], v[88:91]
	v_mfma_f32_16x16x32_bf16 v[88:91], v[170:173], v[214:217], v[88:91]
	v_mfma_f32_16x16x32_bf16 v[76:79], v[128:131], v[218:221], v[76:79]
	v_mfma_f32_16x16x32_bf16 v[76:79], v[150:153], v[222:225], v[76:79]
	v_mfma_f32_16x16x32_bf16 v[72:75], v[166:169], v[218:221], v[72:75]
	v_mfma_f32_16x16x32_bf16 v[72:75], v[170:173], v[222:225], v[72:75]
	s_setprio 0
	s_setprio 2
	v_mfma_f32_16x16x32_bf16 v[116:119], v[174:177], v[190:193], v[116:119]
	v_mfma_f32_16x16x32_bf16 v[116:119], v[178:181], v[194:197], v[116:119]
	v_mfma_f32_16x16x32_bf16 v[112:115], v[182:185], v[190:193], v[112:115]
	v_mfma_f32_16x16x32_bf16 v[112:115], v[186:189], v[194:197], v[112:115]
	v_mfma_f32_16x16x32_bf16 v[100:103], v[174:177], v[198:201], v[100:103]
	v_mfma_f32_16x16x32_bf16 v[100:103], v[178:181], v[206:209], v[100:103]
	v_mfma_f32_16x16x32_bf16 v[96:99], v[182:185], v[198:201], v[96:99]
	v_mfma_f32_16x16x32_bf16 v[96:99], v[186:189], v[206:209], v[96:99]
	v_mfma_f32_16x16x32_bf16 v[84:87], v[174:177], v[210:213], v[84:87]
	v_mfma_f32_16x16x32_bf16 v[84:87], v[178:181], v[214:217], v[84:87]
	v_mfma_f32_16x16x32_bf16 v[80:83], v[182:185], v[210:213], v[80:83]
	v_mfma_f32_16x16x32_bf16 v[80:83], v[186:189], v[214:217], v[80:83]
	v_mfma_f32_16x16x32_bf16 v[68:71], v[174:177], v[218:221], v[68:71]
	v_mfma_f32_16x16x32_bf16 v[68:71], v[178:181], v[222:225], v[68:71]
	v_mfma_f32_16x16x32_bf16 v[64:67], v[182:185], v[218:221], v[64:67]
	s_setprio 3
	s_barrier
	v_mfma_f32_16x16x32_bf16 v[64:67], v[186:189], v[222:225], v[64:67]
	s_setprio 0
	s_add_i32 s92, s82, s67
	v_lshl_add_u64 v[226:227], s[6:7], 0, v[134:135]
	s_mov_b32 m0, s92
	ds_read_b128 v[190:193], v160 offset:16384
	ds_read_b128 v[194:197], v250 offset:16384
	ds_read_b128 v[198:201], v160 offset:18432
	ds_read_b128 v[206:209], v250 offset:18432
	ds_read_b128 v[210:213], v160 offset:20480
	ds_read_b128 v[214:217], v250 offset:20480
	ds_read_b128 v[218:221], v160 offset:22528
	ds_read_b128 v[222:225], v250 offset:22528
	global_load_lds_dwordx4 v[226:227], off
	s_add_i32 m0, s92, 0x2000
	s_add_u32 s92, s6, 0x41000
	v_lshl_add_u64 v[228:229], s[6:7], 0, v[138:139]
	s_addc_u32 s93, s7, 0
	s_add_i32 s94, s83, s67
	global_load_lds_dwordx4 v[228:229], off
	v_lshl_add_u64 v[230:231], s[92:93], 0, v[134:135]
	s_mov_b32 m0, s94
	s_nop 0
	global_load_lds_dwordx4 v[230:231], off
	v_lshl_add_u64 v[230:231], s[92:93], 0, v[138:139]
	s_add_i32 m0, s94, 0x2000
	s_nop 0
	global_load_lds_dwordx4 v[230:231], off
	s_waitcnt vmcnt(6)
	s_waitcnt lgkmcnt(0)
	s_barrier
; #define PG8_STAGE(bufoff, gbase, voff) do { _Pragma("unroll") for (int _i = 0; _i < 2; ++_i) \
;         __builtin_amdgcn_global_load_lds((const unsigned*)((const char*)(gbase) + (voff)[_i]), (LAS unsigned*)(lds + (bufoff) + ldsw + _i * 8192), 16, 0, 0); } while (0)
; #define PG8_LDA(dst, b, h) do { _Pragma("unroll") for (int m = 0; m < 4; ++m) _Pragma("unroll") for (int k = 0; k < 2; ++k) dst[m][k] = *(const LAS bf16x8*)(lds + PG8_SA(b, h) + aoff + m * 2048 + k * 1024); } while (0)
; #define PG8_LDB(dst, b, h) do { _Pragma("unroll") for (int n = 0; n < 2; ++n) _Pragma("unroll") for (int k = 0; k < 2; ++k) dst[n][k] = *(const LAS bf16x8*)(lds + PG8_SB(b, h) + boff + n * 2048 + k * 1024); } while (0)
; #define PG8_MMA(ai, bj, At, Bt) do { __builtin_amdgcn_s_setprio(3); _Pragma("unroll") for (int m = 0; m < 4; ++m) _Pragma("unroll") for (int n = 0; n < 2; ++n) _Pragma("unroll") for (int k = 0; k < 2; ++k) \
;         acc[ai][bj][m][n] = __builtin_amdgcn_mfma_f32_16x16x32_bf16(Bt[n][k], At[m][k], acc[ai][bj][m][n], 0, 0, 0); __builtin_amdgcn_s_setprio(0); } while (0)
; #define PG8_WAIT_V(n) asm volatile("s_waitcnt vmcnt(" #n ")" ::: "memory")
; #define PG8_WAIT_L(n) asm volatile("s_waitcnt lgkmcnt(" #n ")" ::: "memory")
; #define PG8_BAR __builtin_amdgcn_s_barrier()
; #define PG8_SCHED __builtin_amdgcn_sched_barrier(0)
; template <class Epi, class Sched, bool ALIGN_EPI = false, bool SP2 = false>
; __device__ __forceinline__ void gemm_phase(LAS unsigned char* lds, const Gemm g, const Sched& S, const Epi& E) {
;     ...
;             PG8_WAIT_V(8); PG8_WAIT_L(0); PG8_BAR; PG8_MMA(1, 0, At, B0); PG8_MMA(1, 1, At, B1); PG8_BAR; PG8_SCHED;
;             PG8_LDB(B0, 1, 0); PG8_LDB(B1, 1, 1); PG8_SCHED; PG8_LDA(At, 1, 0); PG8_STAGE(PG8_SA(0, 1), a2 + hsA, voffA);
;             PG8_WAIT_V(8); PG8_WAIT_L(0); PG8_BAR; PG8_MMA(0, 0, At, B0); PG8_MMA(0, 1, At, B1); PG8_BAR; PG8_SCHED;
	s_setprio 2
	s_waitcnt lgkmcnt(0)
	v_mfma_f32_16x16x32_bf16 v[60:63], v[128:131], v[190:193], v[60:63]
	v_mfma_f32_16x16x32_bf16 v[60:63], v[150:153], v[194:197], v[60:63]
	v_mfma_f32_16x16x32_bf16 v[56:59], v[166:169], v[190:193], v[56:59]
	v_mfma_f32_16x16x32_bf16 v[56:59], v[170:173], v[194:197], v[56:59]
	v_mfma_f32_16x16x32_bf16 v[44:47], v[128:131], v[198:201], v[44:47]
	v_mfma_f32_16x16x32_bf16 v[44:47], v[150:153], v[206:209], v[44:47]
	v_mfma_f32_16x16x32_bf16 v[40:43], v[166:169], v[198:201], v[40:43]
	v_mfma_f32_16x16x32_bf16 v[40:43], v[170:173], v[206:209], v[40:43]
	v_mfma_f32_16x16x32_bf16 v[28:31], v[128:131], v[210:213], v[28:31]
	v_mfma_f32_16x16x32_bf16 v[28:31], v[150:153], v[214:217], v[28:31]
	v_mfma_f32_16x16x32_bf16 v[24:27], v[166:169], v[210:213], v[24:27]
	v_mfma_f32_16x16x32_bf16 v[24:27], v[170:173], v[214:217], v[24:27]
	v_mfma_f32_16x16x32_bf16 v[12:15], v[128:131], v[218:221], v[12:15]
	v_mfma_f32_16x16x32_bf16 v[12:15], v[150:153], v[222:225], v[12:15]
	v_mfma_f32_16x16x32_bf16 v[8:11], v[166:169], v[218:221], v[8:11]
	v_mfma_f32_16x16x32_bf16 v[8:11], v[170:173], v[222:225], v[8:11]
	s_setprio 0
	s_setprio 2
	v_mfma_f32_16x16x32_bf16 v[52:55], v[174:177], v[190:193], v[52:55]
	v_mfma_f32_16x16x32_bf16 v[52:55], v[178:181], v[194:197], v[52:55]
	v_mfma_f32_16x16x32_bf16 v[48:51], v[182:185], v[190:193], v[48:51]
	v_mfma_f32_16x16x32_bf16 v[48:51], v[186:189], v[194:197], v[48:51]
	v_mfma_f32_16x16x32_bf16 v[36:39], v[174:177], v[198:201], v[36:39]
	v_mfma_f32_16x16x32_bf16 v[36:39], v[178:181], v[206:209], v[36:39]
	v_mfma_f32_16x16x32_bf16 v[32:35], v[182:185], v[198:201], v[32:35]
	v_mfma_f32_16x16x32_bf16 v[32:35], v[186:189], v[206:209], v[32:35]
	v_mfma_f32_16x16x32_bf16 v[20:23], v[174:177], v[210:213], v[20:23]
	v_mfma_f32_16x16x32_bf16 v[20:23], v[178:181], v[214:217], v[20:23]
	v_mfma_f32_16x16x32_bf16 v[16:19], v[182:185], v[210:213], v[16:19]
	v_mfma_f32_16x16x32_bf16 v[16:19], v[186:189], v[214:217], v[16:19]
	v_mfma_f32_16x16x32_bf16 v[4:7], v[174:177], v[218:221], v[4:7]
	v_mfma_f32_16x16x32_bf16 v[4:7], v[178:181], v[222:225], v[4:7]
	v_mfma_f32_16x16x32_bf16 v[0:3], v[182:185], v[218:221], v[0:3]
	s_setprio 3
	s_barrier
	v_mfma_f32_16x16x32_bf16 v[0:3], v[186:189], v[222:225], v[0:3]
	s_setprio 0
	s_add_i32 s92, 0, 0x18000
	v_add_u32_e32 v165, s92, v156
	v_xor_b32_e32 v253, 64, v165
	s_add_i32 s93, 0, 0x1c000
	ds_read_b128 v[128:131], v165
	ds_read_b128 v[150:153], v253
	ds_read_b128 v[166:169], v165 offset:2048
	ds_read_b128 v[170:173], v253 offset:2048
	v_add_u32_e32 v165, s93, v156
	v_xor_b32_e32 v253, 64, v165
	ds_read_b128 v[174:177], v165
	ds_read_b128 v[178:181], v253
	ds_read_b128 v[182:185], v165 offset:2048
	ds_read_b128 v[186:189], v253 offset:2048
	v_lshl_add_u64 v[242:243], s[62:63], 0, v[132:133]
	s_mov_b32 m0, s68
	v_lshl_add_u64 v[244:245], s[62:63], 0, v[136:137]
	global_load_lds_dwordx4 v[242:243], off
	s_mov_b32 m0, s69
	s_nop 0
	global_load_lds_dwordx4 v[244:245], off
	s_add_u32 s62, s62, 0x104000
	s_addc_u32 s63, s63, 0
	s_mov_b32 m0, s70
	v_lshl_add_u64 v[234:235], s[62:63], 0, v[132:133]
	ds_read_b128 v[190:193], v160 offset:32768
	ds_read_b128 v[194:197], v250 offset:32768
	ds_read_b128 v[198:201], v160 offset:34816
	ds_read_b128 v[206:209], v250 offset:34816
	ds_read_b128 v[210:213], v160 offset:36864
	ds_read_b128 v[214:217], v250 offset:36864
	ds_read_b128 v[218:221], v160 offset:38912
	ds_read_b128 v[222:225], v250 offset:38912
	global_load_lds_dwordx4 v[234:235], off
	v_lshl_add_u64 v[234:235], s[62:63], 0, v[136:137]
	s_mov_b32 m0, s71
	s_nop 0
	global_load_lds_dwordx4 v[234:235], off
	s_waitcnt vmcnt(8)
	s_waitcnt lgkmcnt(0)
	s_barrier
; #define PG8_STAGE(bufoff, gbase, voff) do { _Pragma("unroll") for (int _i = 0; _i < 2; ++_i) \
;         __builtin_amdgcn_global_load_lds((const unsigned*)((const char*)(gbase) + (voff)[_i]), (LAS unsigned*)(lds + (bufoff) + ldsw + _i * 8192), 16, 0, 0); } while (0)
; #define PG8_LDA(dst, b, h) do { _Pragma("unroll") for (int m = 0; m < 4; ++m) _Pragma("unroll") for (int k = 0; k < 2; ++k) dst[m][k] = *(const LAS bf16x8*)(lds + PG8_SA(b, h) + aoff + m * 2048 + k * 1024); } while (0)
; #define PG8_MMA(ai, bj, At, Bt) do { __builtin_amdgcn_s_setprio(3); _Pragma("unroll") for (int m = 0; m < 4; ++m) _Pragma("unroll") for (int n = 0; n < 2; ++n) _Pragma("unroll") for (int k = 0; k < 2; ++k) \
;         acc[ai][bj][m][n] = __builtin_amdgcn_mfma_f32_16x16x32_bf16(Bt[n][k], At[m][k], acc[ai][bj][m][n], 0, 0, 0); __builtin_amdgcn_s_setprio(0); } while (0)
; #define PG8_WAIT_V(n) asm volatile("s_waitcnt vmcnt(" #n ")" ::: "memory")
; #define PG8_WAIT_L(n) asm volatile("s_waitcnt lgkmcnt(" #n ")" ::: "memory")
; #define PG8_BAR __builtin_amdgcn_s_barrier()
; #define PG8_SCHED __builtin_amdgcn_sched_barrier(0)
; template <class Epi, class Sched, bool ALIGN_EPI = false, bool SP2 = false>
; __device__ __forceinline__ void gemm_phase(LAS unsigned char* lds, const Gemm g, const Sched& S, const Epi& E) {
;     ...
;             PG8_WAIT_V(8); PG8_WAIT_L(0); PG8_BAR; PG8_MMA(0, 0, At, B0); PG8_MMA(0, 1, At, B1); PG8_BAR; PG8_SCHED;
;             PG8_LDA(At, 1, 1); PG8_STAGE(PG8_SB(1, 0), b3, voffB); PG8_STAGE(PG8_SB(1, 1), b3 + hsB, voffB); PG8_STAGE(PG8_SA(1, 0), a3, voffA);
;             PG8_WAIT_V(8); PG8_WAIT_L(0); PG8_BAR; PG8_MMA(1, 0, At, B0); PG8_MMA(1, 1, At, B1); PG8_BAR; PG8_SCHED;
	s_setprio 2
	s_waitcnt lgkmcnt(0)
	v_mfma_f32_16x16x32_bf16 v[124:127], v[128:131], v[190:193], v[124:127]
	v_mfma_f32_16x16x32_bf16 v[124:127], v[150:153], v[194:197], v[124:127]
	v_mfma_f32_16x16x32_bf16 v[120:123], v[166:169], v[190:193], v[120:123]
	v_mfma_f32_16x16x32_bf16 v[120:123], v[170:173], v[194:197], v[120:123]
	v_mfma_f32_16x16x32_bf16 v[108:111], v[128:131], v[198:201], v[108:111]
	v_mfma_f32_16x16x32_bf16 v[108:111], v[150:153], v[206:209], v[108:111]
	v_mfma_f32_16x16x32_bf16 v[104:107], v[166:169], v[198:201], v[104:107]
	v_mfma_f32_16x16x32_bf16 v[104:107], v[170:173], v[206:209], v[104:107]
	v_mfma_f32_16x16x32_bf16 v[92:95], v[128:131], v[210:213], v[92:95]
	v_mfma_f32_16x16x32_bf16 v[92:95], v[150:153], v[214:217], v[92:95]
	v_mfma_f32_16x16x32_bf16 v[88:91], v[166:169], v[210:213], v[88:91]
	v_mfma_f32_16x16x32_bf16 v[88:91], v[170:173], v[214:217], v[88:91]
	v_mfma_f32_16x16x32_bf16 v[76:79], v[128:131], v[218:221], v[76:79]
	v_mfma_f32_16x16x32_bf16 v[76:79], v[150:153], v[222:225], v[76:79]
	v_mfma_f32_16x16x32_bf16 v[72:75], v[166:169], v[218:221], v[72:75]
	v_mfma_f32_16x16x32_bf16 v[72:75], v[170:173], v[222:225], v[72:75]
	s_setprio 0
	s_setprio 2
	v_mfma_f32_16x16x32_bf16 v[116:119], v[174:177], v[190:193], v[116:119]
	v_mfma_f32_16x16x32_bf16 v[116:119], v[178:181], v[194:197], v[116:119]
	v_mfma_f32_16x16x32_bf16 v[112:115], v[182:185], v[190:193], v[112:115]
	v_mfma_f32_16x16x32_bf16 v[112:115], v[186:189], v[194:197], v[112:115]
	v_mfma_f32_16x16x32_bf16 v[100:103], v[174:177], v[198:201], v[100:103]
	v_mfma_f32_16x16x32_bf16 v[100:103], v[178:181], v[206:209], v[100:103]
	v_mfma_f32_16x16x32_bf16 v[96:99], v[182:185], v[198:201], v[96:99]
	v_mfma_f32_16x16x32_bf16 v[96:99], v[186:189], v[206:209], v[96:99]
	v_mfma_f32_16x16x32_bf16 v[84:87], v[174:177], v[210:213], v[84:87]
	v_mfma_f32_16x16x32_bf16 v[84:87], v[178:181], v[214:217], v[84:87]
	v_mfma_f32_16x16x32_bf16 v[80:83], v[182:185], v[210:213], v[80:83]
	v_mfma_f32_16x16x32_bf16 v[80:83], v[186:189], v[214:217], v[80:83]
	v_mfma_f32_16x16x32_bf16 v[68:71], v[174:177], v[218:221], v[68:71]
	v_mfma_f32_16x16x32_bf16 v[68:71], v[178:181], v[222:225], v[68:71]
	v_mfma_f32_16x16x32_bf16 v[64:67], v[182:185], v[218:221], v[64:67]
	s_setprio 3
	s_barrier
	v_mfma_f32_16x16x32_bf16 v[64:67], v[186:189], v[222:225], v[64:67]
	s_setprio 0
	s_add_i32 s62, s92, s67
	v_lshl_add_u64 v[226:227], v[226:227], 0, s[46:47]
	s_mov_b32 m0, s62
	ds_read_b128 v[190:193], v160 offset:49152
	ds_read_b128 v[194:197], v250 offset:49152
	ds_read_b128 v[198:201], v160 offset:51200
	ds_read_b128 v[206:209], v250 offset:51200
	ds_read_b128 v[210:213], v160 offset:53248
	ds_read_b128 v[214:217], v250 offset:53248
	ds_read_b128 v[218:221], v160 offset:55296
	ds_read_b128 v[222:225], v250 offset:55296
	global_load_lds_dwordx4 v[226:227], off
	s_add_i32 m0, s62, 0x2000
	s_add_u32 s6, s6, 0x41080
	v_lshl_add_u64 v[226:227], v[228:229], 0, s[46:47]
	s_addc_u32 s7, s7, 0
	s_add_i32 s62, s93, s67
	global_load_lds_dwordx4 v[226:227], off
	v_lshl_add_u64 v[226:227], s[6:7], 0, v[134:135]
	s_mov_b32 m0, s62
	s_nop 0
	global_load_lds_dwordx4 v[226:227], off
	v_lshl_add_u64 v[226:227], s[6:7], 0, v[138:139]
	s_add_i32 m0, s62, 0x2000
	s_nop 0
	global_load_lds_dwordx4 v[226:227], off
	s_waitcnt vmcnt(6)
	s_waitcnt lgkmcnt(0)
	s_barrier
	s_setprio 2
	s_waitcnt lgkmcnt(0)
	v_mfma_f32_16x16x32_bf16 v[60:63], v[128:131], v[190:193], v[60:63]
	v_mfma_f32_16x16x32_bf16 v[60:63], v[150:153], v[194:197], v[60:63]
	v_mfma_f32_16x16x32_bf16 v[56:59], v[166:169], v[190:193], v[56:59]
	v_mfma_f32_16x16x32_bf16 v[56:59], v[170:173], v[194:197], v[56:59]
	v_mfma_f32_16x16x32_bf16 v[44:47], v[128:131], v[198:201], v[44:47]
	v_mfma_f32_16x16x32_bf16 v[44:47], v[150:153], v[206:209], v[44:47]
	v_mfma_f32_16x16x32_bf16 v[40:43], v[166:169], v[198:201], v[40:43]
	v_mfma_f32_16x16x32_bf16 v[40:43], v[170:173], v[206:209], v[40:43]
	v_mfma_f32_16x16x32_bf16 v[28:31], v[128:131], v[210:213], v[28:31]
	v_mfma_f32_16x16x32_bf16 v[28:31], v[150:153], v[214:217], v[28:31]
	v_mfma_f32_16x16x32_bf16 v[24:27], v[166:169], v[210:213], v[24:27]
	v_mfma_f32_16x16x32_bf16 v[24:27], v[170:173], v[214:217], v[24:27]
	v_mfma_f32_16x16x32_bf16 v[12:15], v[128:131], v[218:221], v[12:15]
	v_mfma_f32_16x16x32_bf16 v[12:15], v[150:153], v[222:225], v[12:15]
	v_mfma_f32_16x16x32_bf16 v[8:11], v[166:169], v[218:221], v[8:11]
	v_mfma_f32_16x16x32_bf16 v[8:11], v[170:173], v[222:225], v[8:11]
	s_setprio 0
	s_setprio 2
	v_mfma_f32_16x16x32_bf16 v[52:55], v[174:177], v[190:193], v[52:55]
	v_mfma_f32_16x16x32_bf16 v[52:55], v[178:181], v[194:197], v[52:55]
	v_mfma_f32_16x16x32_bf16 v[48:51], v[182:185], v[190:193], v[48:51]
	v_mfma_f32_16x16x32_bf16 v[48:51], v[186:189], v[194:197], v[48:51]
	v_mfma_f32_16x16x32_bf16 v[36:39], v[174:177], v[198:201], v[36:39]
	v_mfma_f32_16x16x32_bf16 v[36:39], v[178:181], v[206:209], v[36:39]
	v_mfma_f32_16x16x32_bf16 v[32:35], v[182:185], v[198:201], v[32:35]
	v_mfma_f32_16x16x32_bf16 v[32:35], v[186:189], v[206:209], v[32:35]
	v_mfma_f32_16x16x32_bf16 v[20:23], v[174:177], v[210:213], v[20:23]
	v_mfma_f32_16x16x32_bf16 v[20:23], v[178:181], v[214:217], v[20:23]
	v_mfma_f32_16x16x32_bf16 v[16:19], v[182:185], v[210:213], v[16:19]
	v_mfma_f32_16x16x32_bf16 v[16:19], v[186:189], v[214:217], v[16:19]
	v_mfma_f32_16x16x32_bf16 v[4:7], v[174:177], v[218:221], v[4:7]
	v_mfma_f32_16x16x32_bf16 v[4:7], v[178:181], v[222:225], v[4:7]
	v_mfma_f32_16x16x32_bf16 v[0:3], v[182:185], v[218:221], v[0:3]
	s_setprio 3
	s_barrier
	v_mfma_f32_16x16x32_bf16 v[0:3], v[186:189], v[222:225], v[0:3]
	s_setprio 0
	s_add_i32 s91, s91, 2
	s_add_u32 s4, s4, 0x100
	s_addc_u32 s5, s5, 0
	s_add_u32 s89, s89, 0x100
	s_addc_u32 s90, s90, 0
	s_cmp_gt_u32 s91, 61
	s_cbranch_scc0 .LBB0_64
	s_and_b64 vcc, exec, s[50:51]
	s_cbranch_vccz .LBB0_67
	s_barrier

; #define PG8_STAGE(bufoff, gbase, voff) do { _Pragma("unroll") for (int _i = 0; _i < 2; ++_i) \
;         __builtin_amdgcn_global_load_lds((const unsigned*)((const char*)(gbase) + (voff)[_i]), (LAS unsigned*)(lds + (bufoff) + ldsw + _i * 8192), 16, 0, 0); } while (0)
; #define PG8_LDA(dst, b, h) do { _Pragma("unroll") for (int m = 0; m < 4; ++m) _Pragma("unroll") for (int k = 0; k < 2; ++k) dst[m][k] = *(const LAS bf16x8*)(lds + PG8_SA(b, h) + aoff + m * 2048 + k * 1024); } while (0)
; #define PG8_LDB(dst, b, h) do { _Pragma("unroll") for (int n = 0; n < 2; ++n) _Pragma("unroll") for (int k = 0; k < 2; ++k) dst[n][k] = *(const LAS bf16x8*)(lds + PG8_SB(b, h) + boff + n * 2048 + k * 1024); } while (0)
; #define PG8_MMA(ai, bj, At, Bt) do { __builtin_amdgcn_s_setprio(3); _Pragma("unroll") for (int m = 0; m < 4; ++m) _Pragma("unroll") for (int n = 0; n < 2; ++n) _Pragma("unroll") for (int k = 0; k < 2; ++k) \
;         acc[ai][bj][m][n] = __builtin_amdgcn_mfma_f32_16x16x32_bf16(Bt[n][k], At[m][k], acc[ai][bj][m][n], 0, 0, 0); __builtin_amdgcn_s_setprio(0); } while (0)
; #define PG8_WAIT_V(n) asm volatile("s_waitcnt vmcnt(" #n ")" ::: "memory")
; #define PG8_WAIT_L(n) asm volatile("s_waitcnt lgkmcnt(" #n ")" ::: "memory")
; #define PG8_BAR __builtin_amdgcn_s_barrier()
; template <class Epi, class Sched, bool ALIGN_EPI = false, bool SP2 = false>
; __device__ __forceinline__ void gemm_phase(LAS unsigned char* lds, const Gemm g, const Sched& S, const Epi& E) {
;     ...
;             const char* a2 = last ? nA : cA + (size_t)(t + 2) * kstep; const char* b2 = last ? nB : cB + (size_t)(t + 2) * kstep;
;             const char* a3 = a2 + kstep; const char* b3 = b2 + kstep;
;             if (last && has_next) S.a_ready(nxt);
;             if constexpr (Epi::MID) { if (t == nt / 2) E.mid(acc, cur, wr, wc, fr, fq); }
;             if constexpr (SP2) {
;             PG8_LDB(B0, 0, 0); PG8_LDB(B1, 0, 1); PG8_SCHED; PG8_LDA(At, 0, 0); PG8_STAGE(PG8_SA(1, 1), a1 + hsA, voffA);
;             PG8_WAIT_V(8); PG8_WAIT_L(0); PG8_BAR; PG8_MMA(0, 0, At, B0); PG8_MMA(0, 1, At, B1); PG8_BAR; PG8_SCHED;
;             PG8_LDA(At, 0, 1); PG8_STAGE(PG8_SB(0, 0), b2, voffB); PG8_STAGE(PG8_SB(0, 1), b2 + hsB, voffB); PG8_STAGE(PG8_SA(0, 0), a2, voffA);
;             PG8_WAIT_V(8); PG8_WAIT_L(0); PG8_BAR; PG8_MMA(1, 0, At, B0); PG8_MMA(1, 1, At, B1); PG8_BAR; PG8_SCHED;
.LBB0_234:
	v_add_u32_e32 v1, s88, v194
	v_xor_b32_e32 v253, 64, v1
	ds_read_b128 v[84:87], v1
	ds_read_b128 v[96:99], v253
	ds_read_b128 v[140:143], v1 offset:2048
	ds_read_b128 v[144:147], v253 offset:2048
	v_add_u32_e32 v1, s89, v194
	v_xor_b32_e32 v253, 64, v1
	s_add_u32 s4, s64, s66
	ds_read_b128 v[152:155], v1
	ds_read_b128 v[156:159], v253
	ds_read_b128 v[160:163], v1 offset:2048
	ds_read_b128 v[182:185], v253 offset:2048
	s_addc_u32 s5, s65, s67
	s_add_u32 s4, s4, 0x100
	s_addc_u32 s5, s5, 0
	s_add_u32 s96, s93, s66
	s_addc_u32 s97, s94, s67
	s_cmpk_eq_i32 s66, 0x1f00
	s_cselect_b32 s9, s59, s5
	s_cselect_b32 s8, s91, s4
	s_cselect_b32 s5, s61, s97
	s_cselect_b32 s4, s60, s96
	s_sub_u32 s100, s66, 0x100000
	s_subb_u32 s101, s67, 0
	v_lshl_add_u64 v[242:243], v[148:149], 0, s[100:101]
	s_mov_b32 m0, s81
	v_lshl_add_u64 v[244:245], v[150:151], 0, s[100:101]
	global_load_lds_dwordx4 v[242:243], off
	s_mov_b32 m0, s82
	s_nop 0
	global_load_lds_dwordx4 v[244:245], off
	v_lshl_add_u64 v[2:3], v[148:149], 0, s[66:67]
	s_add_i32 m0, s41, 0xc000
	ds_read_b128 v[186:189], v198
	ds_read_b128 v[208:211], v250
	ds_read_b128 v[212:215], v198 offset:2048
	ds_read_b128 v[216:219], v250 offset:2048
	ds_read_b128 v[220:223], v198 offset:4096
	ds_read_b128 v[224:227], v250 offset:4096
	ds_read_b128 v[228:231], v198 offset:6144
	ds_read_b128 v[232:235], v250 offset:6144
	global_load_lds_dwordx4 v[2:3], off
	v_lshl_add_u64 v[2:3], v[150:151], 0, s[66:67]
	s_add_i32 m0, s41, 0xe000
	s_nop 0
	global_load_lds_dwordx4 v[2:3], off
	s_waitcnt vmcnt(8)
	s_waitcnt lgkmcnt(0)
	s_barrier
	s_setprio 2
	s_waitcnt lgkmcnt(0)
	v_mfma_f32_16x16x32_bf16 v[136:139], v[84:87], v[186:189], v[136:139]
	v_mfma_f32_16x16x32_bf16 v[136:139], v[96:99], v[208:211], v[136:139]
	v_mfma_f32_16x16x32_bf16 v[132:135], v[140:143], v[186:189], v[132:135]
	v_mfma_f32_16x16x32_bf16 v[132:135], v[144:147], v[208:211], v[132:135]
	v_mfma_f32_16x16x32_bf16 v[120:123], v[84:87], v[212:215], v[120:123]
	v_mfma_f32_16x16x32_bf16 v[120:123], v[96:99], v[216:219], v[120:123]
	v_mfma_f32_16x16x32_bf16 v[116:119], v[140:143], v[212:215], v[116:119]
	v_mfma_f32_16x16x32_bf16 v[116:119], v[144:147], v[216:219], v[116:119]
	v_mfma_f32_16x16x32_bf16 v[104:107], v[84:87], v[220:223], v[104:107]
	v_mfma_f32_16x16x32_bf16 v[104:107], v[96:99], v[224:227], v[104:107]
	v_mfma_f32_16x16x32_bf16 v[100:103], v[140:143], v[220:223], v[100:103]
	v_mfma_f32_16x16x32_bf16 v[100:103], v[144:147], v[224:227], v[100:103]
	v_mfma_f32_16x16x32_bf16 v[80:83], v[84:87], v[228:231], v[80:83]
	v_mfma_f32_16x16x32_bf16 v[80:83], v[96:99], v[232:235], v[80:83]
	v_mfma_f32_16x16x32_bf16 v[76:79], v[140:143], v[228:231], v[76:79]
	v_mfma_f32_16x16x32_bf16 v[76:79], v[144:147], v[232:235], v[76:79]
	s_setprio 0
	s_setprio 2
	v_mfma_f32_16x16x32_bf16 v[128:131], v[152:155], v[186:189], v[128:131]
	v_mfma_f32_16x16x32_bf16 v[128:131], v[156:159], v[208:211], v[128:131]
	v_mfma_f32_16x16x32_bf16 v[124:127], v[160:163], v[186:189], v[124:127]
	v_mfma_f32_16x16x32_bf16 v[124:127], v[182:185], v[208:211], v[124:127]
	v_mfma_f32_16x16x32_bf16 v[112:115], v[152:155], v[212:215], v[112:115]
	v_mfma_f32_16x16x32_bf16 v[112:115], v[156:159], v[216:219], v[112:115]
	v_mfma_f32_16x16x32_bf16 v[108:111], v[160:163], v[212:215], v[108:111]
	v_mfma_f32_16x16x32_bf16 v[108:111], v[182:185], v[216:219], v[108:111]
	v_mfma_f32_16x16x32_bf16 v[92:95], v[152:155], v[220:223], v[92:95]
	v_mfma_f32_16x16x32_bf16 v[92:95], v[156:159], v[224:227], v[92:95]
	v_mfma_f32_16x16x32_bf16 v[88:91], v[160:163], v[220:223], v[88:91]
	v_mfma_f32_16x16x32_bf16 v[88:91], v[182:185], v[224:227], v[88:91]
	v_mfma_f32_16x16x32_bf16 v[72:75], v[152:155], v[228:231], v[72:75]
	v_mfma_f32_16x16x32_bf16 v[72:75], v[156:159], v[232:235], v[72:75]
	v_mfma_f32_16x16x32_bf16 v[68:71], v[160:163], v[228:231], v[68:71]
	s_setprio 3
	s_barrier
	v_mfma_f32_16x16x32_bf16 v[68:71], v[182:185], v[232:235], v[68:71]
	s_setprio 0
	s_add_i32 s96, s88, s31
	v_lshl_add_u64 v[190:191], s[4:5], 0, v[166:167]
	s_mov_b32 m0, s96
	ds_read_b128 v[186:189], v198 offset:16384
	ds_read_b128 v[208:211], v250 offset:16384
	ds_read_b128 v[212:215], v198 offset:18432
	ds_read_b128 v[216:219], v250 offset:18432
	ds_read_b128 v[220:223], v198 offset:20480
	ds_read_b128 v[224:227], v250 offset:20480
	ds_read_b128 v[228:231], v198 offset:22528
	ds_read_b128 v[232:235], v250 offset:22528
	global_load_lds_dwordx4 v[190:191], off
	s_add_i32 m0, s96, 0x2000
	s_add_u32 s96, s4, 0x104000
	v_lshl_add_u64 v[236:237], s[4:5], 0, v[170:171]
	s_addc_u32 s97, s5, 0
	s_add_i32 s98, s89, s31
	global_load_lds_dwordx4 v[236:237], off
	v_lshl_add_u64 v[2:3], s[96:97], 0, v[166:167]
	s_mov_b32 m0, s98
	s_nop 0
	global_load_lds_dwordx4 v[2:3], off
	v_lshl_add_u64 v[2:3], s[96:97], 0, v[170:171]
	s_add_i32 m0, s98, 0x2000
	s_nop 0
	global_load_lds_dwordx4 v[2:3], off
	s_waitcnt vmcnt(6)
	s_waitcnt lgkmcnt(0)
	s_barrier
; #define PG8_STAGE(bufoff, gbase, voff) do { _Pragma("unroll") for (int _i = 0; _i < 2; ++_i) \
;         __builtin_amdgcn_global_load_lds((const unsigned*)((const char*)(gbase) + (voff)[_i]), (LAS unsigned*)(lds + (bufoff) + ldsw + _i * 8192), 16, 0, 0); } while (0)
; #define PG8_LDA(dst, b, h) do { _Pragma("unroll") for (int m = 0; m < 4; ++m) _Pragma("unroll") for (int k = 0; k < 2; ++k) dst[m][k] = *(const LAS bf16x8*)(lds + PG8_SA(b, h) + aoff + m * 2048 + k * 1024); } while (0)
; #define PG8_LDB(dst, b, h) do { _Pragma("unroll") for (int n = 0; n < 2; ++n) _Pragma("unroll") for (int k = 0; k < 2; ++k) dst[n][k] = *(const LAS bf16x8*)(lds + PG8_SB(b, h) + boff + n * 2048 + k * 1024); } while (0)
; #define PG8_MMA(ai, bj, At, Bt) do { __builtin_amdgcn_s_setprio(3); _Pragma("unroll") for (int m = 0; m < 4; ++m) _Pragma("unroll") for (int n = 0; n < 2; ++n) _Pragma("unroll") for (int k = 0; k < 2; ++k) \
;         acc[ai][bj][m][n] = __builtin_amdgcn_mfma_f32_16x16x32_bf16(Bt[n][k], At[m][k], acc[ai][bj][m][n], 0, 0, 0); __builtin_amdgcn_s_setprio(0); } while (0)
; #define PG8_WAIT_V(n) asm volatile("s_waitcnt vmcnt(" #n ")" ::: "memory")
; #define PG8_WAIT_L(n) asm volatile("s_waitcnt lgkmcnt(" #n ")" ::: "memory")
; #define PG8_BAR __builtin_amdgcn_s_barrier()
; #define PG8_SCHED __builtin_amdgcn_sched_barrier(0)
; template <class Epi, class Sched, bool ALIGN_EPI = false, bool SP2 = false>
; __device__ __forceinline__ void gemm_phase(LAS unsigned char* lds, const Gemm g, const Sched& S, const Epi& E) {
;     ...
;             PG8_WAIT_V(8); PG8_WAIT_L(0); PG8_BAR; PG8_MMA(1, 0, At, B0); PG8_MMA(1, 1, At, B1); PG8_BAR; PG8_SCHED;
;             PG8_LDB(B0, 1, 0); PG8_LDB(B1, 1, 1); PG8_SCHED; PG8_LDA(At, 1, 0); PG8_STAGE(PG8_SA(0, 1), a2 + hsA, voffA);
;             PG8_WAIT_V(8); PG8_WAIT_L(0); PG8_BAR; PG8_MMA(0, 0, At, B0); PG8_MMA(0, 1, At, B1); PG8_BAR; PG8_SCHED;
	s_setprio 2
	s_waitcnt lgkmcnt(0)
	v_mfma_f32_16x16x32_bf16 v[64:67], v[84:87], v[186:189], v[64:67]
	v_mfma_f32_16x16x32_bf16 v[64:67], v[96:99], v[208:211], v[64:67]
	v_mfma_f32_16x16x32_bf16 v[60:63], v[140:143], v[186:189], v[60:63]
	v_mfma_f32_16x16x32_bf16 v[60:63], v[144:147], v[208:211], v[60:63]
	v_mfma_f32_16x16x32_bf16 v[48:51], v[84:87], v[212:215], v[48:51]
	v_mfma_f32_16x16x32_bf16 v[48:51], v[96:99], v[216:219], v[48:51]
	v_mfma_f32_16x16x32_bf16 v[44:47], v[140:143], v[212:215], v[44:47]
	v_mfma_f32_16x16x32_bf16 v[44:47], v[144:147], v[216:219], v[44:47]
	v_mfma_f32_16x16x32_bf16 v[32:35], v[84:87], v[220:223], v[32:35]
	v_mfma_f32_16x16x32_bf16 v[32:35], v[96:99], v[224:227], v[32:35]
	v_mfma_f32_16x16x32_bf16 v[28:31], v[140:143], v[220:223], v[28:31]
	v_mfma_f32_16x16x32_bf16 v[28:31], v[144:147], v[224:227], v[28:31]
	v_mfma_f32_16x16x32_bf16 v[16:19], v[84:87], v[228:231], v[16:19]
	v_mfma_f32_16x16x32_bf16 v[16:19], v[96:99], v[232:235], v[16:19]
	v_mfma_f32_16x16x32_bf16 v[12:15], v[140:143], v[228:231], v[12:15]
	v_mfma_f32_16x16x32_bf16 v[12:15], v[144:147], v[232:235], v[12:15]
	s_setprio 0
	s_setprio 2
	v_mfma_f32_16x16x32_bf16 v[56:59], v[152:155], v[186:189], v[56:59]
	v_mfma_f32_16x16x32_bf16 v[56:59], v[156:159], v[208:211], v[56:59]
	v_mfma_f32_16x16x32_bf16 v[52:55], v[160:163], v[186:189], v[52:55]
	v_mfma_f32_16x16x32_bf16 v[52:55], v[182:185], v[208:211], v[52:55]
	v_mfma_f32_16x16x32_bf16 v[40:43], v[152:155], v[212:215], v[40:43]
	v_mfma_f32_16x16x32_bf16 v[40:43], v[156:159], v[216:219], v[40:43]
	v_mfma_f32_16x16x32_bf16 v[36:39], v[160:163], v[212:215], v[36:39]
	v_mfma_f32_16x16x32_bf16 v[36:39], v[182:185], v[216:219], v[36:39]
	v_mfma_f32_16x16x32_bf16 v[24:27], v[152:155], v[220:223], v[24:27]
	v_mfma_f32_16x16x32_bf16 v[24:27], v[156:159], v[224:227], v[24:27]
	v_mfma_f32_16x16x32_bf16 v[20:23], v[160:163], v[220:223], v[20:23]
	v_mfma_f32_16x16x32_bf16 v[20:23], v[182:185], v[224:227], v[20:23]
	v_mfma_f32_16x16x32_bf16 v[8:11], v[152:155], v[228:231], v[8:11]
	v_mfma_f32_16x16x32_bf16 v[8:11], v[156:159], v[232:235], v[8:11]
	v_mfma_f32_16x16x32_bf16 v[2:5], v[160:163], v[228:231], v[4:7]
	s_setprio 3
	s_barrier
	v_mfma_f32_16x16x32_bf16 v[2:5], v[182:185], v[232:235], v[2:5]
	s_setprio 0
	s_add_i32 s96, 0, 0x18000
	v_add_u32_e32 v1, s96, v194
	v_xor_b32_e32 v253, 64, v1
	s_add_i32 s97, 0, 0x1c000
	ds_read_b128 v[84:87], v1
	ds_read_b128 v[96:99], v253
	ds_read_b128 v[140:143], v1 offset:2048
	ds_read_b128 v[144:147], v253 offset:2048
	v_add_u32_e32 v1, s97, v194
	v_xor_b32_e32 v253, 64, v1
	ds_read_b128 v[152:155], v1
	ds_read_b128 v[156:159], v253
	ds_read_b128 v[160:163], v1 offset:2048
	ds_read_b128 v[182:185], v253 offset:2048
	v_lshl_add_u64 v[242:243], s[8:9], 0, v[164:165]
	s_mov_b32 m0, s41
	v_lshl_add_u64 v[244:245], s[8:9], 0, v[168:169]
	global_load_lds_dwordx4 v[242:243], off
	s_mov_b32 m0, s68
	s_nop 0
	global_load_lds_dwordx4 v[244:245], off
	s_add_u32 s8, s8, 0x100000
	s_addc_u32 s9, s9, 0
	s_mov_b32 m0, s69
	v_lshl_add_u64 v[6:7], s[8:9], 0, v[164:165]
	ds_read_b128 v[186:189], v198 offset:32768
	ds_read_b128 v[208:211], v250 offset:32768
	ds_read_b128 v[212:215], v198 offset:34816
	ds_read_b128 v[216:219], v250 offset:34816
	ds_read_b128 v[220:223], v198 offset:36864
	ds_read_b128 v[224:227], v250 offset:36864
	ds_read_b128 v[228:231], v198 offset:38912
	ds_read_b128 v[232:235], v250 offset:38912
	global_load_lds_dwordx4 v[6:7], off
	v_lshl_add_u64 v[6:7], s[8:9], 0, v[168:169]
	s_mov_b32 m0, s70
	s_nop 0
	global_load_lds_dwordx4 v[6:7], off
	s_waitcnt vmcnt(8)
	s_waitcnt lgkmcnt(0)
	s_barrier
; #define PG8_STAGE(bufoff, gbase, voff) do { _Pragma("unroll") for (int _i = 0; _i < 2; ++_i) \
;         __builtin_amdgcn_global_load_lds((const unsigned*)((const char*)(gbase) + (voff)[_i]), (LAS unsigned*)(lds + (bufoff) + ldsw + _i * 8192), 16, 0, 0); } while (0)
; #define PG8_LDA(dst, b, h) do { _Pragma("unroll") for (int m = 0; m < 4; ++m) _Pragma("unroll") for (int k = 0; k < 2; ++k) dst[m][k] = *(const LAS bf16x8*)(lds + PG8_SA(b, h) + aoff + m * 2048 + k * 1024); } while (0)
; #define PG8_MMA(ai, bj, At, Bt) do { __builtin_amdgcn_s_setprio(3); _Pragma("unroll") for (int m = 0; m < 4; ++m) _Pragma("unroll") for (int n = 0; n < 2; ++n) _Pragma("unroll") for (int k = 0; k < 2; ++k) \
;         acc[ai][bj][m][n] = __builtin_amdgcn_mfma_f32_16x16x32_bf16(Bt[n][k], At[m][k], acc[ai][bj][m][n], 0, 0, 0); __builtin_amdgcn_s_setprio(0); } while (0)
; #define PG8_WAIT_V(n) asm volatile("s_waitcnt vmcnt(" #n ")" ::: "memory")
; #define PG8_WAIT_L(n) asm volatile("s_waitcnt lgkmcnt(" #n ")" ::: "memory")
; #define PG8_BAR __builtin_amdgcn_s_barrier()
; #define PG8_SCHED __builtin_amdgcn_sched_barrier(0)
; template <class Epi, class Sched, bool ALIGN_EPI = false, bool SP2 = false>
; __device__ __forceinline__ void gemm_phase(LAS unsigned char* lds, const Gemm g, const Sched& S, const Epi& E) {
;     ...
;             PG8_WAIT_V(8); PG8_WAIT_L(0); PG8_BAR; PG8_MMA(0, 0, At, B0); PG8_MMA(0, 1, At, B1); PG8_BAR; PG8_SCHED;
;             PG8_LDA(At, 1, 1); PG8_STAGE(PG8_SB(1, 0), b3, voffB); PG8_STAGE(PG8_SB(1, 1), b3 + hsB, voffB); PG8_STAGE(PG8_SA(1, 0), a3, voffA);
;             PG8_WAIT_V(8); PG8_WAIT_L(0); PG8_BAR; PG8_MMA(1, 0, At, B0); PG8_MMA(1, 1, At, B1); PG8_BAR; PG8_SCHED;
	s_setprio 2
	s_waitcnt lgkmcnt(0)
	v_mfma_f32_16x16x32_bf16 v[136:139], v[84:87], v[186:189], v[136:139]
	v_mfma_f32_16x16x32_bf16 v[136:139], v[96:99], v[208:211], v[136:139]
	v_mfma_f32_16x16x32_bf16 v[132:135], v[140:143], v[186:189], v[132:135]
	v_mfma_f32_16x16x32_bf16 v[132:135], v[144:147], v[208:211], v[132:135]
	v_mfma_f32_16x16x32_bf16 v[120:123], v[84:87], v[212:215], v[120:123]
	v_mfma_f32_16x16x32_bf16 v[120:123], v[96:99], v[216:219], v[120:123]
	v_mfma_f32_16x16x32_bf16 v[116:119], v[140:143], v[212:215], v[116:119]
	v_mfma_f32_16x16x32_bf16 v[116:119], v[144:147], v[216:219], v[116:119]
	v_mfma_f32_16x16x32_bf16 v[104:107], v[84:87], v[220:223], v[104:107]
	v_mfma_f32_16x16x32_bf16 v[104:107], v[96:99], v[224:227], v[104:107]
	v_mfma_f32_16x16x32_bf16 v[100:103], v[140:143], v[220:223], v[100:103]
	v_mfma_f32_16x16x32_bf16 v[100:103], v[144:147], v[224:227], v[100:103]
	v_mfma_f32_16x16x32_bf16 v[80:83], v[84:87], v[228:231], v[80:83]
	v_mfma_f32_16x16x32_bf16 v[80:83], v[96:99], v[232:235], v[80:83]
	v_mfma_f32_16x16x32_bf16 v[76:79], v[140:143], v[228:231], v[76:79]
	v_mfma_f32_16x16x32_bf16 v[76:79], v[144:147], v[232:235], v[76:79]
	s_setprio 0
	s_setprio 2
	v_mfma_f32_16x16x32_bf16 v[128:131], v[152:155], v[186:189], v[128:131]
	v_mfma_f32_16x16x32_bf16 v[128:131], v[156:159], v[208:211], v[128:131]
	v_mfma_f32_16x16x32_bf16 v[124:127], v[160:163], v[186:189], v[124:127]
	v_mfma_f32_16x16x32_bf16 v[124:127], v[182:185], v[208:211], v[124:127]
	v_mfma_f32_16x16x32_bf16 v[112:115], v[152:155], v[212:215], v[112:115]
	v_mfma_f32_16x16x32_bf16 v[112:115], v[156:159], v[216:219], v[112:115]
	v_mfma_f32_16x16x32_bf16 v[108:111], v[160:163], v[212:215], v[108:111]
	v_mfma_f32_16x16x32_bf16 v[108:111], v[182:185], v[216:219], v[108:111]
	v_mfma_f32_16x16x32_bf16 v[92:95], v[152:155], v[220:223], v[92:95]
	v_mfma_f32_16x16x32_bf16 v[92:95], v[156:159], v[224:227], v[92:95]
	v_mfma_f32_16x16x32_bf16 v[88:91], v[160:163], v[220:223], v[88:91]
	v_mfma_f32_16x16x32_bf16 v[88:91], v[182:185], v[224:227], v[88:91]
	v_mfma_f32_16x16x32_bf16 v[72:75], v[152:155], v[228:231], v[72:75]
	v_mfma_f32_16x16x32_bf16 v[72:75], v[156:159], v[232:235], v[72:75]
	v_mfma_f32_16x16x32_bf16 v[68:71], v[160:163], v[228:231], v[68:71]
	s_setprio 3
	s_barrier
	v_mfma_f32_16x16x32_bf16 v[68:71], v[182:185], v[232:235], v[68:71]
	s_setprio 0
	s_add_i32 s8, s96, s31
	v_lshl_add_u64 v[6:7], v[190:191], 0, s[24:25]
	s_mov_b32 m0, s8
	ds_read_b128 v[186:189], v198 offset:49152
	ds_read_b128 v[208:211], v250 offset:49152
	ds_read_b128 v[212:215], v198 offset:51200
	ds_read_b128 v[216:219], v250 offset:51200
	ds_read_b128 v[220:223], v198 offset:53248
	ds_read_b128 v[224:227], v250 offset:53248
	ds_read_b128 v[228:231], v198 offset:55296
	ds_read_b128 v[232:235], v250 offset:55296
	global_load_lds_dwordx4 v[6:7], off
	s_add_i32 m0, s8, 0x2000
	s_add_u32 s4, s4, 0x104080
	v_lshl_add_u64 v[6:7], v[236:237], 0, s[24:25]
	s_addc_u32 s5, s5, 0
	s_add_i32 s8, s97, s31
	global_load_lds_dwordx4 v[6:7], off
	v_lshl_add_u64 v[6:7], s[4:5], 0, v[166:167]
	s_mov_b32 m0, s8
	s_nop 0
	global_load_lds_dwordx4 v[6:7], off
	v_lshl_add_u64 v[6:7], s[4:5], 0, v[170:171]
	s_add_i32 m0, s8, 0x2000
	s_nop 0
	global_load_lds_dwordx4 v[6:7], off
	s_waitcnt vmcnt(6)
	s_waitcnt lgkmcnt(0)
	s_barrier
	s_setprio 2
	s_waitcnt lgkmcnt(0)
	v_mfma_f32_16x16x32_bf16 v[64:67], v[84:87], v[186:189], v[64:67]
	v_mfma_f32_16x16x32_bf16 v[64:67], v[96:99], v[208:211], v[64:67]
	v_mfma_f32_16x16x32_bf16 v[60:63], v[140:143], v[186:189], v[60:63]
	v_mfma_f32_16x16x32_bf16 v[60:63], v[144:147], v[208:211], v[60:63]
	v_mfma_f32_16x16x32_bf16 v[48:51], v[84:87], v[212:215], v[48:51]
	v_mfma_f32_16x16x32_bf16 v[48:51], v[96:99], v[216:219], v[48:51]
	v_mfma_f32_16x16x32_bf16 v[44:47], v[140:143], v[212:215], v[44:47]
	v_mfma_f32_16x16x32_bf16 v[44:47], v[144:147], v[216:219], v[44:47]
	v_mfma_f32_16x16x32_bf16 v[32:35], v[84:87], v[220:223], v[32:35]
	v_mfma_f32_16x16x32_bf16 v[32:35], v[96:99], v[224:227], v[32:35]
	v_mfma_f32_16x16x32_bf16 v[28:31], v[140:143], v[220:223], v[28:31]
	v_mfma_f32_16x16x32_bf16 v[28:31], v[144:147], v[224:227], v[28:31]
	v_mfma_f32_16x16x32_bf16 v[16:19], v[84:87], v[228:231], v[16:19]
	v_mfma_f32_16x16x32_bf16 v[16:19], v[96:99], v[232:235], v[16:19]
	v_mfma_f32_16x16x32_bf16 v[12:15], v[140:143], v[228:231], v[12:15]
	v_mfma_f32_16x16x32_bf16 v[12:15], v[144:147], v[232:235], v[12:15]
	s_setprio 0
	s_setprio 2
	v_mfma_f32_16x16x32_bf16 v[56:59], v[152:155], v[186:189], v[56:59]
	v_mfma_f32_16x16x32_bf16 v[56:59], v[156:159], v[208:211], v[56:59]
	v_mfma_f32_16x16x32_bf16 v[52:55], v[160:163], v[186:189], v[52:55]
	v_mfma_f32_16x16x32_bf16 v[52:55], v[182:185], v[208:211], v[52:55]
	v_mfma_f32_16x16x32_bf16 v[40:43], v[152:155], v[212:215], v[40:43]
	v_mfma_f32_16x16x32_bf16 v[40:43], v[156:159], v[216:219], v[40:43]
	v_mfma_f32_16x16x32_bf16 v[36:39], v[160:163], v[212:215], v[36:39]
	v_mfma_f32_16x16x32_bf16 v[36:39], v[182:185], v[216:219], v[36:39]
	v_mfma_f32_16x16x32_bf16 v[24:27], v[152:155], v[220:223], v[24:27]
	v_mfma_f32_16x16x32_bf16 v[24:27], v[156:159], v[224:227], v[24:27]
	v_mfma_f32_16x16x32_bf16 v[20:23], v[160:163], v[220:223], v[20:23]
	v_mfma_f32_16x16x32_bf16 v[20:23], v[182:185], v[224:227], v[20:23]
	v_mfma_f32_16x16x32_bf16 v[6:9], v[152:155], v[228:231], v[8:11]
	v_mfma_f32_16x16x32_bf16 v[8:11], v[156:159], v[232:235], v[6:9]
	v_mfma_f32_16x16x32_bf16 v[2:5], v[160:163], v[228:231], v[2:5]
	s_setprio 3
	s_barrier
	v_mfma_f32_16x16x32_bf16 v[4:7], v[182:185], v[232:235], v[2:5]
	s_setprio 0
	s_add_i32 s95, s95, 2
	s_add_u32 s66, s66, 0x100
	s_addc_u32 s67, s67, 0
	s_cmp_gt_u32 s95, 61
	s_cbranch_scc1 .LBB0_237

; #define PG8_STAGE(bufoff, gbase, voff) do { _Pragma("unroll") for (int _i = 0; _i < 2; ++_i) \
;         __builtin_amdgcn_global_load_lds((const unsigned*)((const char*)(gbase) + (voff)[_i]), (LAS unsigned*)(lds + (bufoff) + ldsw + _i * 8192), 16, 0, 0); } while (0)
; #define PG8_LDA(dst, b, h) do { _Pragma("unroll") for (int m = 0; m < 4; ++m) _Pragma("unroll") for (int k = 0; k < 2; ++k) dst[m][k] = *(const LAS bf16x8*)(lds + PG8_SA(b, h) + aoff + m * 2048 + k * 1024); } while (0)
; #define PG8_LDB(dst, b, h) do { _Pragma("unroll") for (int n = 0; n < 2; ++n) _Pragma("unroll") for (int k = 0; k < 2; ++k) dst[n][k] = *(const LAS bf16x8*)(lds + PG8_SB(b, h) + boff + n * 2048 + k * 1024); } while (0)
; #define PG8_MMA(ai, bj, At, Bt) do { __builtin_amdgcn_s_setprio(3); _Pragma("unroll") for (int m = 0; m < 4; ++m) _Pragma("unroll") for (int n = 0; n < 2; ++n) _Pragma("unroll") for (int k = 0; k < 2; ++k) \
;         acc[ai][bj][m][n] = __builtin_amdgcn_mfma_f32_16x16x32_bf16(Bt[n][k], At[m][k], acc[ai][bj][m][n], 0, 0, 0); __builtin_amdgcn_s_setprio(0); } while (0)
; #define PG8_WAIT_V(n) asm volatile("s_waitcnt vmcnt(" #n ")" ::: "memory")
; #define PG8_WAIT_L(n) asm volatile("s_waitcnt lgkmcnt(" #n ")" ::: "memory")
; #define PG8_BAR __builtin_amdgcn_s_barrier()
; template <class Epi, class Sched, bool ALIGN_EPI = false, bool SP2 = false>
; __device__ __forceinline__ void gemm_phase(LAS unsigned char* lds, const Gemm g, const Sched& S, const Epi& E) {
;     ...
;             const char* a2 = last ? nA : cA + (size_t)(t + 2) * kstep; const char* b2 = last ? nB : cB + (size_t)(t + 2) * kstep;
;             const char* a3 = a2 + kstep; const char* b3 = b2 + kstep;
;             if (last && has_next) S.a_ready(nxt);
;             if constexpr (Epi::MID) { if (t == nt / 2) E.mid(acc, cur, wr, wc, fr, fq); }
;             if constexpr (SP2) {
;             PG8_LDB(B0, 0, 0); PG8_LDB(B1, 0, 1); PG8_SCHED; PG8_LDA(At, 0, 0); PG8_STAGE(PG8_SA(1, 1), a1 + hsA, voffA);
;             PG8_WAIT_V(8); PG8_WAIT_L(0); PG8_BAR; PG8_MMA(0, 0, At, B0); PG8_MMA(0, 1, At, B1); PG8_BAR; PG8_SCHED;
;             PG8_LDA(At, 0, 1); PG8_STAGE(PG8_SB(0, 0), b2, voffB); PG8_STAGE(PG8_SB(0, 1), b2 + hsB, voffB); PG8_STAGE(PG8_SA(0, 0), a2, voffA);
;             PG8_WAIT_V(8); PG8_WAIT_L(0); PG8_BAR; PG8_MMA(1, 0, At, B0); PG8_MMA(1, 1, At, B1); PG8_BAR; PG8_SCHED;
.LBB0_309:
	ds_read_b128 v[112:115], v175
	ds_read_b128 v[132:135], v251
	ds_read_b128 v[136:139], v175 offset:2048
	ds_read_b128 v[140:143], v251 offset:2048
	ds_read_b128 v[144:147], v176
	ds_read_b128 v[148:151], v252
	ds_read_b128 v[184:187], v176 offset:2048
	ds_read_b128 v[188:191], v252 offset:2048
	s_add_u32 s24, s4, 0xffefc080
	s_addc_u32 s25, s5, -1
	s_cmp_eq_u32 s73, 60
	s_cselect_b32 s27, s11, s25
	s_cselect_b32 s26, s10, s24
	s_cselect_b32 s25, s21, s72
	s_cselect_b32 s24, s20, s71
	s_sub_u32 s100, s4, 0x104000
	s_subb_u32 s101, s5, 0
	v_lshl_add_u64 v[242:243], s[100:101], 0, v[152:153]
	s_mov_b32 m0, s42
	v_lshl_add_u64 v[244:245], s[100:101], 0, v[156:157]
	global_load_lds_dwordx4 v[242:243], off
	s_mov_b32 m0, s43
	s_nop 0
	global_load_lds_dwordx4 v[244:245], off
	v_lshl_add_u64 v[200:201], s[4:5], 0, v[164:165]
	s_add_i32 m0, s36, 0xc000
	ds_read_b128 v[192:195], v177
	ds_read_b128 v[196:199], v250
	ds_read_b128 v[206:209], v177 offset:2048
	ds_read_b128 v[210:213], v250 offset:2048
	ds_read_b128 v[214:217], v177 offset:4096
	ds_read_b128 v[218:221], v250 offset:4096
	ds_read_b128 v[222:225], v177 offset:6144
	ds_read_b128 v[226:229], v250 offset:6144
	global_load_lds_dwordx4 v[200:201], off
	v_lshl_add_u64 v[200:201], s[4:5], 0, v[166:167]
	s_add_i32 m0, s36, 0xe000
	s_nop 0
	global_load_lds_dwordx4 v[200:201], off
	s_waitcnt vmcnt(8)
	s_waitcnt lgkmcnt(0)
	s_barrier
	s_setprio 2
	s_waitcnt lgkmcnt(0)
	v_mfma_f32_16x16x32_bf16 v[128:131], v[112:115], v[192:195], v[128:131]
	v_mfma_f32_16x16x32_bf16 v[128:131], v[132:135], v[196:199], v[128:131]
	v_mfma_f32_16x16x32_bf16 v[124:127], v[136:139], v[192:195], v[124:127]
	v_mfma_f32_16x16x32_bf16 v[124:127], v[140:143], v[196:199], v[124:127]
	v_mfma_f32_16x16x32_bf16 v[108:111], v[112:115], v[206:209], v[108:111]
	v_mfma_f32_16x16x32_bf16 v[108:111], v[132:135], v[210:213], v[108:111]
	v_mfma_f32_16x16x32_bf16 v[104:107], v[136:139], v[206:209], v[104:107]
	v_mfma_f32_16x16x32_bf16 v[104:107], v[140:143], v[210:213], v[104:107]
	v_mfma_f32_16x16x32_bf16 v[92:95], v[112:115], v[214:217], v[92:95]
	v_mfma_f32_16x16x32_bf16 v[92:95], v[132:135], v[218:221], v[92:95]
	v_mfma_f32_16x16x32_bf16 v[88:91], v[136:139], v[214:217], v[88:91]
	v_mfma_f32_16x16x32_bf16 v[88:91], v[140:143], v[218:221], v[88:91]
	v_mfma_f32_16x16x32_bf16 v[76:79], v[112:115], v[222:225], v[76:79]
	v_mfma_f32_16x16x32_bf16 v[76:79], v[132:135], v[226:229], v[76:79]
	v_mfma_f32_16x16x32_bf16 v[72:75], v[136:139], v[222:225], v[72:75]
	v_mfma_f32_16x16x32_bf16 v[72:75], v[140:143], v[226:229], v[72:75]
	s_setprio 0
	s_setprio 2
	v_mfma_f32_16x16x32_bf16 v[120:123], v[144:147], v[192:195], v[120:123]
	v_mfma_f32_16x16x32_bf16 v[120:123], v[148:151], v[196:199], v[120:123]
	v_mfma_f32_16x16x32_bf16 v[116:119], v[184:187], v[192:195], v[116:119]
	v_mfma_f32_16x16x32_bf16 v[116:119], v[188:191], v[196:199], v[116:119]
	v_mfma_f32_16x16x32_bf16 v[100:103], v[144:147], v[206:209], v[100:103]
	v_mfma_f32_16x16x32_bf16 v[100:103], v[148:151], v[210:213], v[100:103]
	v_mfma_f32_16x16x32_bf16 v[96:99], v[184:187], v[206:209], v[96:99]
	v_mfma_f32_16x16x32_bf16 v[96:99], v[188:191], v[210:213], v[96:99]
	v_mfma_f32_16x16x32_bf16 v[84:87], v[144:147], v[214:217], v[84:87]
	v_mfma_f32_16x16x32_bf16 v[84:87], v[148:151], v[218:221], v[84:87]
	v_mfma_f32_16x16x32_bf16 v[80:83], v[184:187], v[214:217], v[80:83]
	v_mfma_f32_16x16x32_bf16 v[80:83], v[188:191], v[218:221], v[80:83]
	v_mfma_f32_16x16x32_bf16 v[68:71], v[144:147], v[222:225], v[68:71]
	v_mfma_f32_16x16x32_bf16 v[68:71], v[148:151], v[226:229], v[68:71]
	v_mfma_f32_16x16x32_bf16 v[64:67], v[184:187], v[222:225], v[64:67]
	s_setprio 3
	s_barrier
	v_mfma_f32_16x16x32_bf16 v[64:67], v[188:191], v[226:229], v[64:67]
	s_setprio 0
	s_add_i32 s74, s45, s31
	v_lshl_add_u64 v[200:201], s[24:25], 0, v[154:155]
	s_mov_b32 m0, s74
	ds_read_b128 v[192:195], v177 offset:16384
	ds_read_b128 v[196:199], v250 offset:16384
	ds_read_b128 v[206:209], v177 offset:18432
	ds_read_b128 v[210:213], v250 offset:18432
	ds_read_b128 v[214:217], v177 offset:20480
	ds_read_b128 v[218:221], v250 offset:20480
	ds_read_b128 v[222:225], v177 offset:22528
	ds_read_b128 v[226:229], v250 offset:22528
	global_load_lds_dwordx4 v[200:201], off
	s_add_i32 m0, s74, 0x2000
	s_add_u32 s74, s24, 0x41000
	v_lshl_add_u64 v[230:231], s[24:25], 0, v[158:159]
	s_addc_u32 s75, s25, 0
	s_add_i32 s78, s46, s31
	global_load_lds_dwordx4 v[230:231], off
	v_lshl_add_u64 v[232:233], s[74:75], 0, v[154:155]
	s_mov_b32 m0, s78
	s_nop 0
	global_load_lds_dwordx4 v[232:233], off
	v_lshl_add_u64 v[232:233], s[74:75], 0, v[158:159]
	s_add_i32 m0, s78, 0x2000
	s_nop 0
	global_load_lds_dwordx4 v[232:233], off
	s_waitcnt vmcnt(6)
	s_waitcnt lgkmcnt(0)
	s_barrier
; #define PG8_STAGE(bufoff, gbase, voff) do { _Pragma("unroll") for (int _i = 0; _i < 2; ++_i) \
;         __builtin_amdgcn_global_load_lds((const unsigned*)((const char*)(gbase) + (voff)[_i]), (LAS unsigned*)(lds + (bufoff) + ldsw + _i * 8192), 16, 0, 0); } while (0)
; #define PG8_LDA(dst, b, h) do { _Pragma("unroll") for (int m = 0; m < 4; ++m) _Pragma("unroll") for (int k = 0; k < 2; ++k) dst[m][k] = *(const LAS bf16x8*)(lds + PG8_SA(b, h) + aoff + m * 2048 + k * 1024); } while (0)
; #define PG8_LDB(dst, b, h) do { _Pragma("unroll") for (int n = 0; n < 2; ++n) _Pragma("unroll") for (int k = 0; k < 2; ++k) dst[n][k] = *(const LAS bf16x8*)(lds + PG8_SB(b, h) + boff + n * 2048 + k * 1024); } while (0)
; #define PG8_MMA(ai, bj, At, Bt) do { __builtin_amdgcn_s_setprio(3); _Pragma("unroll") for (int m = 0; m < 4; ++m) _Pragma("unroll") for (int n = 0; n < 2; ++n) _Pragma("unroll") for (int k = 0; k < 2; ++k) \
;         acc[ai][bj][m][n] = __builtin_amdgcn_mfma_f32_16x16x32_bf16(Bt[n][k], At[m][k], acc[ai][bj][m][n], 0, 0, 0); __builtin_amdgcn_s_setprio(0); } while (0)
; #define PG8_WAIT_V(n) asm volatile("s_waitcnt vmcnt(" #n ")" ::: "memory")
; #define PG8_WAIT_L(n) asm volatile("s_waitcnt lgkmcnt(" #n ")" ::: "memory")
; #define PG8_BAR __builtin_amdgcn_s_barrier()
; #define PG8_SCHED __builtin_amdgcn_sched_barrier(0)
; template <class Epi, class Sched, bool ALIGN_EPI = false, bool SP2 = false>
; __device__ __forceinline__ void gemm_phase(LAS unsigned char* lds, const Gemm g, const Sched& S, const Epi& E) {
;     ...
;             PG8_WAIT_V(8); PG8_WAIT_L(0); PG8_BAR; PG8_MMA(1, 0, At, B0); PG8_MMA(1, 1, At, B1); PG8_BAR; PG8_SCHED;
;             PG8_LDB(B0, 1, 0); PG8_LDB(B1, 1, 1); PG8_SCHED; PG8_LDA(At, 1, 0); PG8_STAGE(PG8_SA(0, 1), a2 + hsA, voffA);
;             PG8_WAIT_V(8); PG8_WAIT_L(0); PG8_BAR; PG8_MMA(0, 0, At, B0); PG8_MMA(0, 1, At, B1); PG8_BAR; PG8_SCHED;
	s_setprio 2
	s_waitcnt lgkmcnt(0)
	v_mfma_f32_16x16x32_bf16 v[60:63], v[112:115], v[192:195], v[60:63]
	v_mfma_f32_16x16x32_bf16 v[60:63], v[132:135], v[196:199], v[60:63]
	v_mfma_f32_16x16x32_bf16 v[56:59], v[136:139], v[192:195], v[56:59]
	v_mfma_f32_16x16x32_bf16 v[56:59], v[140:143], v[196:199], v[56:59]
	v_mfma_f32_16x16x32_bf16 v[44:47], v[112:115], v[206:209], v[44:47]
	v_mfma_f32_16x16x32_bf16 v[44:47], v[132:135], v[210:213], v[44:47]
	v_mfma_f32_16x16x32_bf16 v[40:43], v[136:139], v[206:209], v[40:43]
	v_mfma_f32_16x16x32_bf16 v[40:43], v[140:143], v[210:213], v[40:43]
	v_mfma_f32_16x16x32_bf16 v[28:31], v[112:115], v[214:217], v[28:31]
	v_mfma_f32_16x16x32_bf16 v[28:31], v[132:135], v[218:221], v[28:31]
	v_mfma_f32_16x16x32_bf16 v[24:27], v[136:139], v[214:217], v[24:27]
	v_mfma_f32_16x16x32_bf16 v[24:27], v[140:143], v[218:221], v[24:27]
	v_mfma_f32_16x16x32_bf16 v[12:15], v[112:115], v[222:225], v[12:15]
	v_mfma_f32_16x16x32_bf16 v[12:15], v[132:135], v[226:229], v[12:15]
	v_mfma_f32_16x16x32_bf16 v[8:11], v[136:139], v[222:225], v[8:11]
	v_mfma_f32_16x16x32_bf16 v[8:11], v[140:143], v[226:229], v[8:11]
	s_setprio 0
	s_setprio 2
	v_mfma_f32_16x16x32_bf16 v[52:55], v[144:147], v[192:195], v[52:55]
	v_mfma_f32_16x16x32_bf16 v[52:55], v[148:151], v[196:199], v[52:55]
	v_mfma_f32_16x16x32_bf16 v[48:51], v[184:187], v[192:195], v[48:51]
	v_mfma_f32_16x16x32_bf16 v[48:51], v[188:191], v[196:199], v[48:51]
	v_mfma_f32_16x16x32_bf16 v[36:39], v[144:147], v[206:209], v[36:39]
	v_mfma_f32_16x16x32_bf16 v[36:39], v[148:151], v[210:213], v[36:39]
	v_mfma_f32_16x16x32_bf16 v[32:35], v[184:187], v[206:209], v[32:35]
	v_mfma_f32_16x16x32_bf16 v[32:35], v[188:191], v[210:213], v[32:35]
	v_mfma_f32_16x16x32_bf16 v[20:23], v[144:147], v[214:217], v[20:23]
	v_mfma_f32_16x16x32_bf16 v[20:23], v[148:151], v[218:221], v[20:23]
	v_mfma_f32_16x16x32_bf16 v[16:19], v[184:187], v[214:217], v[16:19]
	v_mfma_f32_16x16x32_bf16 v[16:19], v[188:191], v[218:221], v[16:19]
	v_mfma_f32_16x16x32_bf16 v[4:7], v[144:147], v[222:225], v[4:7]
	v_mfma_f32_16x16x32_bf16 v[4:7], v[148:151], v[226:229], v[4:7]
	v_mfma_f32_16x16x32_bf16 v[0:3], v[184:187], v[222:225], v[0:3]
	s_setprio 3
	s_barrier
	v_mfma_f32_16x16x32_bf16 v[0:3], v[188:191], v[226:229], v[0:3]
	s_setprio 0
	s_add_i32 s74, 0, 0x18000
	s_add_i32 s75, 0, 0x1c000
	v_add_u32_e32 v140, s74, v173
	v_xor_b32_e32 v253, 64, v140
	v_add_u32_e32 v188, s75, v173
	v_xor_b32_e32 v254, 64, v188
	ds_read_b128 v[112:115], v140
	ds_read_b128 v[132:135], v253
	ds_read_b128 v[136:139], v140 offset:2048
	ds_read_b128 v[140:143], v253 offset:2048
	ds_read_b128 v[144:147], v188
	ds_read_b128 v[148:151], v254
	ds_read_b128 v[184:187], v188 offset:2048
	ds_read_b128 v[188:191], v254 offset:2048
	v_lshl_add_u64 v[242:243], s[26:27], 0, v[152:153]
	s_mov_b32 m0, s36
	v_lshl_add_u64 v[244:245], s[26:27], 0, v[156:157]
	global_load_lds_dwordx4 v[242:243], off
	s_mov_b32 m0, s37
	s_nop 0
	global_load_lds_dwordx4 v[244:245], off
	s_add_u32 s26, s26, 0x104000
	s_addc_u32 s27, s27, 0
	s_mov_b32 m0, s38
	v_lshl_add_u64 v[236:237], s[26:27], 0, v[152:153]
	ds_read_b128 v[192:195], v177 offset:32768
	ds_read_b128 v[196:199], v250 offset:32768
	ds_read_b128 v[206:209], v177 offset:34816
	ds_read_b128 v[210:213], v250 offset:34816
	ds_read_b128 v[214:217], v177 offset:36864
	ds_read_b128 v[218:221], v250 offset:36864
	ds_read_b128 v[222:225], v177 offset:38912
	ds_read_b128 v[226:229], v250 offset:38912
	global_load_lds_dwordx4 v[236:237], off
	v_lshl_add_u64 v[236:237], s[26:27], 0, v[156:157]
	s_mov_b32 m0, s39
	s_nop 0
	global_load_lds_dwordx4 v[236:237], off
	s_waitcnt vmcnt(8)
	s_waitcnt lgkmcnt(0)
	s_barrier
; #define PG8_STAGE(bufoff, gbase, voff) do { _Pragma("unroll") for (int _i = 0; _i < 2; ++_i) \
;         __builtin_amdgcn_global_load_lds((const unsigned*)((const char*)(gbase) + (voff)[_i]), (LAS unsigned*)(lds + (bufoff) + ldsw + _i * 8192), 16, 0, 0); } while (0)
; #define PG8_LDA(dst, b, h) do { _Pragma("unroll") for (int m = 0; m < 4; ++m) _Pragma("unroll") for (int k = 0; k < 2; ++k) dst[m][k] = *(const LAS bf16x8*)(lds + PG8_SA(b, h) + aoff + m * 2048 + k * 1024); } while (0)
; #define PG8_MMA(ai, bj, At, Bt) do { __builtin_amdgcn_s_setprio(3); _Pragma("unroll") for (int m = 0; m < 4; ++m) _Pragma("unroll") for (int n = 0; n < 2; ++n) _Pragma("unroll") for (int k = 0; k < 2; ++k) \
;         acc[ai][bj][m][n] = __builtin_amdgcn_mfma_f32_16x16x32_bf16(Bt[n][k], At[m][k], acc[ai][bj][m][n], 0, 0, 0); __builtin_amdgcn_s_setprio(0); } while (0)
; #define PG8_WAIT_V(n) asm volatile("s_waitcnt vmcnt(" #n ")" ::: "memory")
; #define PG8_WAIT_L(n) asm volatile("s_waitcnt lgkmcnt(" #n ")" ::: "memory")
; #define PG8_BAR __builtin_amdgcn_s_barrier()
; #define PG8_SCHED __builtin_amdgcn_sched_barrier(0)
; template <class Epi, class Sched, bool ALIGN_EPI = false, bool SP2 = false>
; __device__ __forceinline__ void gemm_phase(LAS unsigned char* lds, const Gemm g, const Sched& S, const Epi& E) {
;     ...
;             PG8_WAIT_V(8); PG8_WAIT_L(0); PG8_BAR; PG8_MMA(0, 0, At, B0); PG8_MMA(0, 1, At, B1); PG8_BAR; PG8_SCHED;
;             PG8_LDA(At, 1, 1); PG8_STAGE(PG8_SB(1, 0), b3, voffB); PG8_STAGE(PG8_SB(1, 1), b3 + hsB, voffB); PG8_STAGE(PG8_SA(1, 0), a3, voffA);
;             PG8_WAIT_V(8); PG8_WAIT_L(0); PG8_BAR; PG8_MMA(1, 0, At, B0); PG8_MMA(1, 1, At, B1); PG8_BAR; PG8_SCHED;
	s_setprio 2
	s_waitcnt lgkmcnt(0)
	v_mfma_f32_16x16x32_bf16 v[128:131], v[112:115], v[192:195], v[128:131]
	v_mfma_f32_16x16x32_bf16 v[128:131], v[132:135], v[196:199], v[128:131]
	v_mfma_f32_16x16x32_bf16 v[124:127], v[136:139], v[192:195], v[124:127]
	v_mfma_f32_16x16x32_bf16 v[124:127], v[140:143], v[196:199], v[124:127]
	v_mfma_f32_16x16x32_bf16 v[108:111], v[112:115], v[206:209], v[108:111]
	v_mfma_f32_16x16x32_bf16 v[108:111], v[132:135], v[210:213], v[108:111]
	v_mfma_f32_16x16x32_bf16 v[104:107], v[136:139], v[206:209], v[104:107]
	v_mfma_f32_16x16x32_bf16 v[104:107], v[140:143], v[210:213], v[104:107]
	v_mfma_f32_16x16x32_bf16 v[92:95], v[112:115], v[214:217], v[92:95]
	v_mfma_f32_16x16x32_bf16 v[92:95], v[132:135], v[218:221], v[92:95]
	v_mfma_f32_16x16x32_bf16 v[88:91], v[136:139], v[214:217], v[88:91]
	v_mfma_f32_16x16x32_bf16 v[88:91], v[140:143], v[218:221], v[88:91]
	v_mfma_f32_16x16x32_bf16 v[76:79], v[112:115], v[222:225], v[76:79]
	v_mfma_f32_16x16x32_bf16 v[76:79], v[132:135], v[226:229], v[76:79]
	v_mfma_f32_16x16x32_bf16 v[72:75], v[136:139], v[222:225], v[72:75]
	v_mfma_f32_16x16x32_bf16 v[72:75], v[140:143], v[226:229], v[72:75]
	s_setprio 0
	s_setprio 2
	v_mfma_f32_16x16x32_bf16 v[120:123], v[144:147], v[192:195], v[120:123]
	v_mfma_f32_16x16x32_bf16 v[120:123], v[148:151], v[196:199], v[120:123]
	v_mfma_f32_16x16x32_bf16 v[116:119], v[184:187], v[192:195], v[116:119]
	v_mfma_f32_16x16x32_bf16 v[116:119], v[188:191], v[196:199], v[116:119]
	v_mfma_f32_16x16x32_bf16 v[100:103], v[144:147], v[206:209], v[100:103]
	v_mfma_f32_16x16x32_bf16 v[100:103], v[148:151], v[210:213], v[100:103]
	v_mfma_f32_16x16x32_bf16 v[96:99], v[184:187], v[206:209], v[96:99]
	v_mfma_f32_16x16x32_bf16 v[96:99], v[188:191], v[210:213], v[96:99]
	v_mfma_f32_16x16x32_bf16 v[84:87], v[144:147], v[214:217], v[84:87]
	v_mfma_f32_16x16x32_bf16 v[84:87], v[148:151], v[218:221], v[84:87]
	v_mfma_f32_16x16x32_bf16 v[80:83], v[184:187], v[214:217], v[80:83]
	v_mfma_f32_16x16x32_bf16 v[80:83], v[188:191], v[218:221], v[80:83]
	v_mfma_f32_16x16x32_bf16 v[68:71], v[144:147], v[222:225], v[68:71]
	v_mfma_f32_16x16x32_bf16 v[68:71], v[148:151], v[226:229], v[68:71]
	v_mfma_f32_16x16x32_bf16 v[64:67], v[184:187], v[222:225], v[64:67]
	s_setprio 3
	s_barrier
	v_mfma_f32_16x16x32_bf16 v[64:67], v[188:191], v[226:229], v[64:67]
	s_setprio 0
	s_add_i32 s26, s74, s31
	v_lshl_add_u64 v[200:201], v[200:201], 0, s[14:15]
	s_mov_b32 m0, s26
	ds_read_b128 v[192:195], v177 offset:49152
	ds_read_b128 v[196:199], v250 offset:49152
	ds_read_b128 v[206:209], v177 offset:51200
	ds_read_b128 v[210:213], v250 offset:51200
	ds_read_b128 v[214:217], v177 offset:53248
	ds_read_b128 v[218:221], v250 offset:53248
	ds_read_b128 v[222:225], v177 offset:55296
	ds_read_b128 v[226:229], v250 offset:55296
	global_load_lds_dwordx4 v[200:201], off
	s_add_i32 m0, s26, 0x2000
	s_add_u32 s24, s24, 0x41080
	v_lshl_add_u64 v[200:201], v[230:231], 0, s[14:15]
	s_addc_u32 s25, s25, 0
	s_add_i32 s26, s75, s31
	global_load_lds_dwordx4 v[200:201], off
	v_lshl_add_u64 v[200:201], s[24:25], 0, v[154:155]
	s_mov_b32 m0, s26
	s_nop 0
	global_load_lds_dwordx4 v[200:201], off
	v_lshl_add_u64 v[200:201], s[24:25], 0, v[158:159]
	s_add_i32 m0, s26, 0x2000
	s_nop 0
	global_load_lds_dwordx4 v[200:201], off
	s_waitcnt vmcnt(6)
	s_waitcnt lgkmcnt(0)
	s_barrier
	s_setprio 2
	s_waitcnt lgkmcnt(0)
	v_mfma_f32_16x16x32_bf16 v[60:63], v[112:115], v[192:195], v[60:63]
	v_mfma_f32_16x16x32_bf16 v[60:63], v[132:135], v[196:199], v[60:63]
	v_mfma_f32_16x16x32_bf16 v[56:59], v[136:139], v[192:195], v[56:59]
	v_mfma_f32_16x16x32_bf16 v[56:59], v[140:143], v[196:199], v[56:59]
	v_mfma_f32_16x16x32_bf16 v[44:47], v[112:115], v[206:209], v[44:47]
	v_mfma_f32_16x16x32_bf16 v[44:47], v[132:135], v[210:213], v[44:47]
	v_mfma_f32_16x16x32_bf16 v[40:43], v[136:139], v[206:209], v[40:43]
	v_mfma_f32_16x16x32_bf16 v[40:43], v[140:143], v[210:213], v[40:43]
	v_mfma_f32_16x16x32_bf16 v[28:31], v[112:115], v[214:217], v[28:31]
	v_mfma_f32_16x16x32_bf16 v[28:31], v[132:135], v[218:221], v[28:31]
	v_mfma_f32_16x16x32_bf16 v[24:27], v[136:139], v[214:217], v[24:27]
	v_mfma_f32_16x16x32_bf16 v[24:27], v[140:143], v[218:221], v[24:27]
	v_mfma_f32_16x16x32_bf16 v[12:15], v[112:115], v[222:225], v[12:15]
	v_mfma_f32_16x16x32_bf16 v[12:15], v[132:135], v[226:229], v[12:15]
	v_mfma_f32_16x16x32_bf16 v[8:11], v[136:139], v[222:225], v[8:11]
	v_mfma_f32_16x16x32_bf16 v[8:11], v[140:143], v[226:229], v[8:11]
	s_setprio 0
	s_setprio 2
	v_mfma_f32_16x16x32_bf16 v[52:55], v[144:147], v[192:195], v[52:55]
	v_mfma_f32_16x16x32_bf16 v[52:55], v[148:151], v[196:199], v[52:55]
	v_mfma_f32_16x16x32_bf16 v[48:51], v[184:187], v[192:195], v[48:51]
	v_mfma_f32_16x16x32_bf16 v[48:51], v[188:191], v[196:199], v[48:51]
	v_mfma_f32_16x16x32_bf16 v[36:39], v[144:147], v[206:209], v[36:39]
	v_mfma_f32_16x16x32_bf16 v[36:39], v[148:151], v[210:213], v[36:39]
	v_mfma_f32_16x16x32_bf16 v[32:35], v[184:187], v[206:209], v[32:35]
	v_mfma_f32_16x16x32_bf16 v[32:35], v[188:191], v[210:213], v[32:35]
	v_mfma_f32_16x16x32_bf16 v[20:23], v[144:147], v[214:217], v[20:23]
	v_mfma_f32_16x16x32_bf16 v[20:23], v[148:151], v[218:221], v[20:23]
	v_mfma_f32_16x16x32_bf16 v[16:19], v[184:187], v[214:217], v[16:19]
	v_mfma_f32_16x16x32_bf16 v[16:19], v[188:191], v[218:221], v[16:19]
	v_mfma_f32_16x16x32_bf16 v[4:7], v[144:147], v[222:225], v[4:7]
	v_mfma_f32_16x16x32_bf16 v[4:7], v[148:151], v[226:229], v[4:7]
	v_mfma_f32_16x16x32_bf16 v[0:3], v[184:187], v[222:225], v[0:3]
	s_setprio 3
	s_barrier
	v_mfma_f32_16x16x32_bf16 v[0:3], v[188:191], v[226:229], v[0:3]
	s_setprio 0
	s_add_i32 s73, s73, 2
	s_add_u32 s4, s4, 0x100
	s_addc_u32 s5, s5, 0
	s_add_u32 s71, s71, 0x100
	s_addc_u32 s72, s72, 0
	s_cmp_gt_u32 s73, 61
	s_cbranch_scc0 .LBB0_309
	s_and_b64 vcc, exec, s[16:17]
	s_cbranch_vccz .LBB0_312
	s_barrier

; #define PG8_STAGE(bufoff, gbase, voff) do { _Pragma("unroll") for (int _i = 0; _i < 2; ++_i) \
;         __builtin_amdgcn_global_load_lds((const unsigned*)((const char*)(gbase) + (voff)[_i]), (LAS unsigned*)(lds + (bufoff) + ldsw + _i * 8192), 16, 0, 0); } while (0)
; #define PG8_LDA(dst, b, h) do { _Pragma("unroll") for (int m = 0; m < 4; ++m) _Pragma("unroll") for (int k = 0; k < 2; ++k) dst[m][k] = *(const LAS bf16x8*)(lds + PG8_SA(b, h) + aoff + m * 2048 + k * 1024); } while (0)
; #define PG8_LDB(dst, b, h) do { _Pragma("unroll") for (int n = 0; n < 2; ++n) _Pragma("unroll") for (int k = 0; k < 2; ++k) dst[n][k] = *(const LAS bf16x8*)(lds + PG8_SB(b, h) + boff + n * 2048 + k * 1024); } while (0)
; #define PG8_MMA(ai, bj, At, Bt) do { __builtin_amdgcn_s_setprio(3); _Pragma("unroll") for (int m = 0; m < 4; ++m) _Pragma("unroll") for (int n = 0; n < 2; ++n) _Pragma("unroll") for (int k = 0; k < 2; ++k) \
;         acc[ai][bj][m][n] = __builtin_amdgcn_mfma_f32_16x16x32_bf16(Bt[n][k], At[m][k], acc[ai][bj][m][n], 0, 0, 0); __builtin_amdgcn_s_setprio(0); } while (0)
; #define PG8_WAIT_V(n) asm volatile("s_waitcnt vmcnt(" #n ")" ::: "memory")
; #define PG8_WAIT_L(n) asm volatile("s_waitcnt lgkmcnt(" #n ")" ::: "memory")
; #define PG8_BAR __builtin_amdgcn_s_barrier()
; template <class Epi, class Sched, bool ALIGN_EPI = false, bool SP2 = false>
; __device__ __forceinline__ void gemm_phase(LAS unsigned char* lds, const Gemm g, const Sched& S, const Epi& E) {
;     ...
;             const char* a2 = last ? nA : cA + (size_t)(t + 2) * kstep; const char* b2 = last ? nB : cB + (size_t)(t + 2) * kstep;
;             const char* a3 = a2 + kstep; const char* b3 = b2 + kstep;
;             if (last && has_next) S.a_ready(nxt);
;             if constexpr (Epi::MID) { if (t == nt / 2) E.mid(acc, cur, wr, wc, fr, fq); }
;             if constexpr (SP2) {
;             PG8_LDB(B0, 0, 0); PG8_LDB(B1, 0, 1); PG8_SCHED; PG8_LDA(At, 0, 0); PG8_STAGE(PG8_SA(1, 1), a1 + hsA, voffA);
;             PG8_WAIT_V(8); PG8_WAIT_L(0); PG8_BAR; PG8_MMA(0, 0, At, B0); PG8_MMA(0, 1, At, B1); PG8_BAR; PG8_SCHED;
;             PG8_LDA(At, 0, 1); PG8_STAGE(PG8_SB(0, 0), b2, voffB); PG8_STAGE(PG8_SB(0, 1), b2 + hsB, voffB); PG8_STAGE(PG8_SA(0, 0), a2, voffA);
;             PG8_WAIT_V(8); PG8_WAIT_L(0); PG8_BAR; PG8_MMA(1, 0, At, B0); PG8_MMA(1, 1, At, B1); PG8_BAR; PG8_SCHED;
.LBB0_350:
	ds_read_b128 v[140:143], v149
	ds_read_b128 v[156:159], v251
	ds_read_b128 v[160:163], v149 offset:2048
	ds_read_b128 v[164:167], v251 offset:2048
	ds_read_b128 v[168:171], v150
	ds_read_b128 v[172:175], v252
	ds_read_b128 v[176:179], v150 offset:2048
	ds_read_b128 v[180:183], v252 offset:2048
	s_add_u32 s16, s14, 0xffbfc080
	s_addc_u32 s17, s15, -1
	s_cmpk_eq_i32 s50, 0xfc
	s_cselect_b32 s21, s5, s17
	s_cselect_b32 s20, s4, s16
	s_cselect_b32 s17, s13, s49
	s_cselect_b32 s16, s12, s48
	s_sub_u32 s100, s14, 0x404000
	s_subb_u32 s101, s15, 0
	v_lshl_add_u64 v[242:243], s[100:101], 0, v[128:129]
	s_mov_b32 m0, s33
	v_lshl_add_u64 v[244:245], s[100:101], 0, v[130:131]
	global_load_lds_dwordx4 v[242:243], off
	s_mov_b32 m0, s38
	s_nop 0
	global_load_lds_dwordx4 v[244:245], off
	v_lshl_add_u64 v[144:145], s[14:15], 0, v[132:133]
	s_add_i32 m0, s26, 0xc000
	ds_read_b128 v[184:187], v151
	ds_read_b128 v[188:191], v250
	ds_read_b128 v[192:195], v151 offset:2048
	ds_read_b128 v[196:199], v250 offset:2048
	ds_read_b128 v[200:203], v151 offset:4096
	ds_read_b128 v[204:207], v250 offset:4096
	ds_read_b128 v[208:211], v151 offset:6144
	ds_read_b128 v[212:215], v250 offset:6144
	global_load_lds_dwordx4 v[144:145], off
	v_lshl_add_u64 v[144:145], s[14:15], 0, v[134:135]
	s_add_i32 m0, s26, 0xe000
	s_nop 0
	global_load_lds_dwordx4 v[144:145], off
	s_waitcnt vmcnt(8)
	s_waitcnt lgkmcnt(0)
	s_barrier
	s_setprio 2
	s_waitcnt lgkmcnt(0)
	v_mfma_f32_16x16x32_bf16 v[124:127], v[140:143], v[184:187], v[124:127]
	v_mfma_f32_16x16x32_bf16 v[124:127], v[156:159], v[188:191], v[124:127]
	v_mfma_f32_16x16x32_bf16 v[120:123], v[160:163], v[184:187], v[120:123]
	v_mfma_f32_16x16x32_bf16 v[120:123], v[164:167], v[188:191], v[120:123]
	v_mfma_f32_16x16x32_bf16 v[108:111], v[140:143], v[192:195], v[108:111]
	v_mfma_f32_16x16x32_bf16 v[108:111], v[156:159], v[196:199], v[108:111]
	v_mfma_f32_16x16x32_bf16 v[104:107], v[160:163], v[192:195], v[104:107]
	v_mfma_f32_16x16x32_bf16 v[104:107], v[164:167], v[196:199], v[104:107]
	v_mfma_f32_16x16x32_bf16 v[92:95], v[140:143], v[200:203], v[92:95]
	v_mfma_f32_16x16x32_bf16 v[92:95], v[156:159], v[204:207], v[92:95]
	v_mfma_f32_16x16x32_bf16 v[88:91], v[160:163], v[200:203], v[88:91]
	v_mfma_f32_16x16x32_bf16 v[88:91], v[164:167], v[204:207], v[88:91]
	v_mfma_f32_16x16x32_bf16 v[76:79], v[140:143], v[208:211], v[76:79]
	v_mfma_f32_16x16x32_bf16 v[76:79], v[156:159], v[212:215], v[76:79]
	v_mfma_f32_16x16x32_bf16 v[72:75], v[160:163], v[208:211], v[72:75]
	v_mfma_f32_16x16x32_bf16 v[72:75], v[164:167], v[212:215], v[72:75]
	s_setprio 0
	s_setprio 2
	v_mfma_f32_16x16x32_bf16 v[116:119], v[168:171], v[184:187], v[116:119]
	v_mfma_f32_16x16x32_bf16 v[116:119], v[172:175], v[188:191], v[116:119]
	v_mfma_f32_16x16x32_bf16 v[112:115], v[176:179], v[184:187], v[112:115]
	v_mfma_f32_16x16x32_bf16 v[112:115], v[180:183], v[188:191], v[112:115]
	v_mfma_f32_16x16x32_bf16 v[100:103], v[168:171], v[192:195], v[100:103]
	v_mfma_f32_16x16x32_bf16 v[100:103], v[172:175], v[196:199], v[100:103]
	v_mfma_f32_16x16x32_bf16 v[96:99], v[176:179], v[192:195], v[96:99]
	v_mfma_f32_16x16x32_bf16 v[96:99], v[180:183], v[196:199], v[96:99]
	v_mfma_f32_16x16x32_bf16 v[84:87], v[168:171], v[200:203], v[84:87]
	v_mfma_f32_16x16x32_bf16 v[84:87], v[172:175], v[204:207], v[84:87]
	v_mfma_f32_16x16x32_bf16 v[80:83], v[176:179], v[200:203], v[80:83]
	v_mfma_f32_16x16x32_bf16 v[80:83], v[180:183], v[204:207], v[80:83]
	v_mfma_f32_16x16x32_bf16 v[68:71], v[168:171], v[208:211], v[68:71]
	v_mfma_f32_16x16x32_bf16 v[68:71], v[172:175], v[212:215], v[68:71]
	s_setprio 3
	s_barrier
	v_mfma_f32_16x16x32_bf16 v[64:67], v[176:179], v[208:211], v[64:67]
	v_mfma_f32_16x16x32_bf16 v[64:67], v[180:183], v[212:215], v[64:67]
	s_setprio 0
	s_add_i32 s51, s41, s25
	v_lshl_add_u64 v[144:145], s[16:17], 0, v[128:129]
	s_mov_b32 m0, s51
	ds_read_b128 v[184:187], v151 offset:16384
	ds_read_b128 v[188:191], v250 offset:16384
	ds_read_b128 v[192:195], v151 offset:18432
	ds_read_b128 v[196:199], v250 offset:18432
	ds_read_b128 v[200:203], v151 offset:20480
	ds_read_b128 v[204:207], v250 offset:20480
	ds_read_b128 v[208:211], v151 offset:22528
	ds_read_b128 v[212:215], v250 offset:22528
	global_load_lds_dwordx4 v[144:145], off
	s_add_i32 m0, s51, 0x2000
	s_add_u32 s52, s16, 0x404000
	v_lshl_add_u64 v[216:217], s[16:17], 0, v[130:131]
	s_addc_u32 s53, s17, 0
	s_add_i32 s51, s42, s25
	global_load_lds_dwordx4 v[216:217], off
	v_lshl_add_u64 v[218:219], s[52:53], 0, v[128:129]
	s_mov_b32 m0, s51
	s_nop 0
	global_load_lds_dwordx4 v[218:219], off
	v_lshl_add_u64 v[218:219], s[52:53], 0, v[130:131]
	s_add_i32 m0, s51, 0x2000
	s_nop 0
	global_load_lds_dwordx4 v[218:219], off
	s_waitcnt vmcnt(6)
	s_waitcnt lgkmcnt(0)
	s_barrier
; #define PG8_STAGE(bufoff, gbase, voff) do { _Pragma("unroll") for (int _i = 0; _i < 2; ++_i) \
;         __builtin_amdgcn_global_load_lds((const unsigned*)((const char*)(gbase) + (voff)[_i]), (LAS unsigned*)(lds + (bufoff) + ldsw + _i * 8192), 16, 0, 0); } while (0)
; #define PG8_LDA(dst, b, h) do { _Pragma("unroll") for (int m = 0; m < 4; ++m) _Pragma("unroll") for (int k = 0; k < 2; ++k) dst[m][k] = *(const LAS bf16x8*)(lds + PG8_SA(b, h) + aoff + m * 2048 + k * 1024); } while (0)
; #define PG8_LDB(dst, b, h) do { _Pragma("unroll") for (int n = 0; n < 2; ++n) _Pragma("unroll") for (int k = 0; k < 2; ++k) dst[n][k] = *(const LAS bf16x8*)(lds + PG8_SB(b, h) + boff + n * 2048 + k * 1024); } while (0)
; #define PG8_MMA(ai, bj, At, Bt) do { __builtin_amdgcn_s_setprio(3); _Pragma("unroll") for (int m = 0; m < 4; ++m) _Pragma("unroll") for (int n = 0; n < 2; ++n) _Pragma("unroll") for (int k = 0; k < 2; ++k) \
;         acc[ai][bj][m][n] = __builtin_amdgcn_mfma_f32_16x16x32_bf16(Bt[n][k], At[m][k], acc[ai][bj][m][n], 0, 0, 0); __builtin_amdgcn_s_setprio(0); } while (0)
; #define PG8_WAIT_V(n) asm volatile("s_waitcnt vmcnt(" #n ")" ::: "memory")
; #define PG8_WAIT_L(n) asm volatile("s_waitcnt lgkmcnt(" #n ")" ::: "memory")
; #define PG8_BAR __builtin_amdgcn_s_barrier()
; #define PG8_SCHED __builtin_amdgcn_sched_barrier(0)
; template <class Epi, class Sched, bool ALIGN_EPI = false, bool SP2 = false>
; __device__ __forceinline__ void gemm_phase(LAS unsigned char* lds, const Gemm g, const Sched& S, const Epi& E) {
;     ...
;             PG8_WAIT_V(8); PG8_WAIT_L(0); PG8_BAR; PG8_MMA(1, 0, At, B0); PG8_MMA(1, 1, At, B1); PG8_BAR; PG8_SCHED;
;             PG8_LDB(B0, 1, 0); PG8_LDB(B1, 1, 1); PG8_SCHED; PG8_LDA(At, 1, 0); PG8_STAGE(PG8_SA(0, 1), a2 + hsA, voffA);
;             PG8_WAIT_V(8); PG8_WAIT_L(0); PG8_BAR; PG8_MMA(0, 0, At, B0); PG8_MMA(0, 1, At, B1); PG8_BAR; PG8_SCHED;
	s_setprio 2
	s_waitcnt lgkmcnt(0)
	v_mfma_f32_16x16x32_bf16 v[60:63], v[140:143], v[184:187], v[60:63]
	v_mfma_f32_16x16x32_bf16 v[60:63], v[156:159], v[188:191], v[60:63]
	v_mfma_f32_16x16x32_bf16 v[56:59], v[160:163], v[184:187], v[56:59]
	v_mfma_f32_16x16x32_bf16 v[56:59], v[164:167], v[188:191], v[56:59]
	v_mfma_f32_16x16x32_bf16 v[44:47], v[140:143], v[192:195], v[44:47]
	v_mfma_f32_16x16x32_bf16 v[44:47], v[156:159], v[196:199], v[44:47]
	v_mfma_f32_16x16x32_bf16 v[40:43], v[160:163], v[192:195], v[40:43]
	v_mfma_f32_16x16x32_bf16 v[40:43], v[164:167], v[196:199], v[40:43]
	v_mfma_f32_16x16x32_bf16 v[28:31], v[140:143], v[200:203], v[28:31]
	v_mfma_f32_16x16x32_bf16 v[28:31], v[156:159], v[204:207], v[28:31]
	v_mfma_f32_16x16x32_bf16 v[24:27], v[160:163], v[200:203], v[24:27]
	v_mfma_f32_16x16x32_bf16 v[24:27], v[164:167], v[204:207], v[24:27]
	v_mfma_f32_16x16x32_bf16 v[12:15], v[140:143], v[208:211], v[12:15]
	v_mfma_f32_16x16x32_bf16 v[12:15], v[156:159], v[212:215], v[12:15]
	v_mfma_f32_16x16x32_bf16 v[8:11], v[160:163], v[208:211], v[8:11]
	v_mfma_f32_16x16x32_bf16 v[8:11], v[164:167], v[212:215], v[8:11]
	s_setprio 0
	s_setprio 2
	v_mfma_f32_16x16x32_bf16 v[52:55], v[168:171], v[184:187], v[52:55]
	v_mfma_f32_16x16x32_bf16 v[52:55], v[172:175], v[188:191], v[52:55]
	v_mfma_f32_16x16x32_bf16 v[48:51], v[176:179], v[184:187], v[48:51]
	v_mfma_f32_16x16x32_bf16 v[48:51], v[180:183], v[188:191], v[48:51]
	v_mfma_f32_16x16x32_bf16 v[36:39], v[168:171], v[192:195], v[36:39]
	v_mfma_f32_16x16x32_bf16 v[36:39], v[172:175], v[196:199], v[36:39]
	v_mfma_f32_16x16x32_bf16 v[32:35], v[176:179], v[192:195], v[32:35]
	v_mfma_f32_16x16x32_bf16 v[32:35], v[180:183], v[196:199], v[32:35]
	v_mfma_f32_16x16x32_bf16 v[20:23], v[168:171], v[200:203], v[20:23]
	v_mfma_f32_16x16x32_bf16 v[20:23], v[172:175], v[204:207], v[20:23]
	v_mfma_f32_16x16x32_bf16 v[16:19], v[176:179], v[200:203], v[16:19]
	v_mfma_f32_16x16x32_bf16 v[16:19], v[180:183], v[204:207], v[16:19]
	v_mfma_f32_16x16x32_bf16 v[4:7], v[168:171], v[208:211], v[4:7]
	v_mfma_f32_16x16x32_bf16 v[4:7], v[172:175], v[212:215], v[4:7]
	s_setprio 3
	s_barrier
	v_mfma_f32_16x16x32_bf16 v[0:3], v[176:179], v[208:211], v[0:3]
	v_mfma_f32_16x16x32_bf16 v[0:3], v[180:183], v[212:215], v[0:3]
	s_setprio 0
	s_add_i32 s51, 0, 0x18000
	v_add_u32_e32 v155, s51, v146
	v_xor_b32_e32 v253, 64, v155
	s_add_i32 s52, 0, 0x1c000
	ds_read_b128 v[140:143], v155
	ds_read_b128 v[156:159], v253
	ds_read_b128 v[160:163], v155 offset:2048
	ds_read_b128 v[164:167], v253 offset:2048
	v_add_u32_e32 v155, s52, v146
	v_xor_b32_e32 v253, 64, v155
	ds_read_b128 v[168:171], v155
	ds_read_b128 v[172:175], v253
	ds_read_b128 v[176:179], v155 offset:2048
	ds_read_b128 v[180:183], v253 offset:2048
	v_lshl_add_u64 v[242:243], s[20:21], 0, v[128:129]
	s_mov_b32 m0, s26
	v_lshl_add_u64 v[244:245], s[20:21], 0, v[130:131]
	global_load_lds_dwordx4 v[242:243], off
	s_mov_b32 m0, s27
	s_nop 0
	global_load_lds_dwordx4 v[244:245], off
	s_add_u32 s20, s20, 0x404000
	s_addc_u32 s21, s21, 0
	s_mov_b32 m0, s30
	v_lshl_add_u64 v[222:223], s[20:21], 0, v[128:129]
	ds_read_b128 v[184:187], v151 offset:32768
	ds_read_b128 v[188:191], v250 offset:32768
	ds_read_b128 v[192:195], v151 offset:34816
	ds_read_b128 v[196:199], v250 offset:34816
	ds_read_b128 v[200:203], v151 offset:36864
	ds_read_b128 v[204:207], v250 offset:36864
	ds_read_b128 v[208:211], v151 offset:38912
	ds_read_b128 v[212:215], v250 offset:38912
	global_load_lds_dwordx4 v[222:223], off
	v_lshl_add_u64 v[222:223], s[20:21], 0, v[130:131]
	s_mov_b32 m0, s31
	s_nop 0
	global_load_lds_dwordx4 v[222:223], off
	s_waitcnt vmcnt(8)
	s_waitcnt lgkmcnt(0)
	s_barrier
; #define PG8_STAGE(bufoff, gbase, voff) do { _Pragma("unroll") for (int _i = 0; _i < 2; ++_i) \
;         __builtin_amdgcn_global_load_lds((const unsigned*)((const char*)(gbase) + (voff)[_i]), (LAS unsigned*)(lds + (bufoff) + ldsw + _i * 8192), 16, 0, 0); } while (0)
; #define PG8_LDA(dst, b, h) do { _Pragma("unroll") for (int m = 0; m < 4; ++m) _Pragma("unroll") for (int k = 0; k < 2; ++k) dst[m][k] = *(const LAS bf16x8*)(lds + PG8_SA(b, h) + aoff + m * 2048 + k * 1024); } while (0)
; #define PG8_MMA(ai, bj, At, Bt) do { __builtin_amdgcn_s_setprio(3); _Pragma("unroll") for (int m = 0; m < 4; ++m) _Pragma("unroll") for (int n = 0; n < 2; ++n) _Pragma("unroll") for (int k = 0; k < 2; ++k) \
;         acc[ai][bj][m][n] = __builtin_amdgcn_mfma_f32_16x16x32_bf16(Bt[n][k], At[m][k], acc[ai][bj][m][n], 0, 0, 0); __builtin_amdgcn_s_setprio(0); } while (0)
; #define PG8_WAIT_V(n) asm volatile("s_waitcnt vmcnt(" #n ")" ::: "memory")
; #define PG8_WAIT_L(n) asm volatile("s_waitcnt lgkmcnt(" #n ")" ::: "memory")
; #define PG8_BAR __builtin_amdgcn_s_barrier()
; #define PG8_SCHED __builtin_amdgcn_sched_barrier(0)
; template <class Epi, class Sched, bool ALIGN_EPI = false, bool SP2 = false>
; __device__ __forceinline__ void gemm_phase(LAS unsigned char* lds, const Gemm g, const Sched& S, const Epi& E) {
;     ...
;             PG8_WAIT_V(8); PG8_WAIT_L(0); PG8_BAR; PG8_MMA(0, 0, At, B0); PG8_MMA(0, 1, At, B1); PG8_BAR; PG8_SCHED;
;             PG8_LDA(At, 1, 1); PG8_STAGE(PG8_SB(1, 0), b3, voffB); PG8_STAGE(PG8_SB(1, 1), b3 + hsB, voffB); PG8_STAGE(PG8_SA(1, 0), a3, voffA);
;             PG8_WAIT_V(8); PG8_WAIT_L(0); PG8_BAR; PG8_MMA(1, 0, At, B0); PG8_MMA(1, 1, At, B1); PG8_BAR; PG8_SCHED;
	s_setprio 2
	s_waitcnt lgkmcnt(0)
	v_mfma_f32_16x16x32_bf16 v[124:127], v[140:143], v[184:187], v[124:127]
	v_mfma_f32_16x16x32_bf16 v[124:127], v[156:159], v[188:191], v[124:127]
	v_mfma_f32_16x16x32_bf16 v[120:123], v[160:163], v[184:187], v[120:123]
	v_mfma_f32_16x16x32_bf16 v[120:123], v[164:167], v[188:191], v[120:123]
	v_mfma_f32_16x16x32_bf16 v[108:111], v[140:143], v[192:195], v[108:111]
	v_mfma_f32_16x16x32_bf16 v[108:111], v[156:159], v[196:199], v[108:111]
	v_mfma_f32_16x16x32_bf16 v[104:107], v[160:163], v[192:195], v[104:107]
	v_mfma_f32_16x16x32_bf16 v[104:107], v[164:167], v[196:199], v[104:107]
	v_mfma_f32_16x16x32_bf16 v[92:95], v[140:143], v[200:203], v[92:95]
	v_mfma_f32_16x16x32_bf16 v[92:95], v[156:159], v[204:207], v[92:95]
	v_mfma_f32_16x16x32_bf16 v[88:91], v[160:163], v[200:203], v[88:91]
	v_mfma_f32_16x16x32_bf16 v[88:91], v[164:167], v[204:207], v[88:91]
	v_mfma_f32_16x16x32_bf16 v[76:79], v[140:143], v[208:211], v[76:79]
	v_mfma_f32_16x16x32_bf16 v[76:79], v[156:159], v[212:215], v[76:79]
	v_mfma_f32_16x16x32_bf16 v[72:75], v[160:163], v[208:211], v[72:75]
	v_mfma_f32_16x16x32_bf16 v[72:75], v[164:167], v[212:215], v[72:75]
	s_setprio 0
	s_setprio 2
	v_mfma_f32_16x16x32_bf16 v[116:119], v[168:171], v[184:187], v[116:119]
	v_mfma_f32_16x16x32_bf16 v[116:119], v[172:175], v[188:191], v[116:119]
	v_mfma_f32_16x16x32_bf16 v[112:115], v[176:179], v[184:187], v[112:115]
	v_mfma_f32_16x16x32_bf16 v[112:115], v[180:183], v[188:191], v[112:115]
	v_mfma_f32_16x16x32_bf16 v[100:103], v[168:171], v[192:195], v[100:103]
	v_mfma_f32_16x16x32_bf16 v[100:103], v[172:175], v[196:199], v[100:103]
	v_mfma_f32_16x16x32_bf16 v[96:99], v[176:179], v[192:195], v[96:99]
	v_mfma_f32_16x16x32_bf16 v[96:99], v[180:183], v[196:199], v[96:99]
	v_mfma_f32_16x16x32_bf16 v[84:87], v[168:171], v[200:203], v[84:87]
	v_mfma_f32_16x16x32_bf16 v[84:87], v[172:175], v[204:207], v[84:87]
	v_mfma_f32_16x16x32_bf16 v[80:83], v[176:179], v[200:203], v[80:83]
	v_mfma_f32_16x16x32_bf16 v[80:83], v[180:183], v[204:207], v[80:83]
	v_mfma_f32_16x16x32_bf16 v[68:71], v[168:171], v[208:211], v[68:71]
	v_mfma_f32_16x16x32_bf16 v[68:71], v[172:175], v[212:215], v[68:71]
	s_setprio 3
	s_barrier
	v_mfma_f32_16x16x32_bf16 v[64:67], v[176:179], v[208:211], v[64:67]
	v_mfma_f32_16x16x32_bf16 v[64:67], v[180:183], v[212:215], v[64:67]
	s_setprio 0
	s_add_i32 s20, s51, s25
	v_lshl_add_u64 v[144:145], v[144:145], 0, s[8:9]
	s_mov_b32 m0, s20
	ds_read_b128 v[184:187], v151 offset:49152
	ds_read_b128 v[188:191], v250 offset:49152
	ds_read_b128 v[192:195], v151 offset:51200
	ds_read_b128 v[196:199], v250 offset:51200
	ds_read_b128 v[200:203], v151 offset:53248
	ds_read_b128 v[204:207], v250 offset:53248
	ds_read_b128 v[208:211], v151 offset:55296
	ds_read_b128 v[212:215], v250 offset:55296
	global_load_lds_dwordx4 v[144:145], off
	s_add_i32 m0, s20, 0x2000
	s_add_u32 s16, s16, 0x404080
	v_lshl_add_u64 v[144:145], v[216:217], 0, s[8:9]
	s_addc_u32 s17, s17, 0
	s_add_i32 s20, s52, s25
	global_load_lds_dwordx4 v[144:145], off
	v_lshl_add_u64 v[144:145], s[16:17], 0, v[128:129]
	s_mov_b32 m0, s20
	s_nop 0
	global_load_lds_dwordx4 v[144:145], off
	v_lshl_add_u64 v[144:145], s[16:17], 0, v[130:131]
	s_add_i32 m0, s20, 0x2000
	s_nop 0
	global_load_lds_dwordx4 v[144:145], off
	s_waitcnt vmcnt(6)
	s_waitcnt lgkmcnt(0)
	s_barrier
	s_setprio 2
	s_waitcnt lgkmcnt(0)
	v_mfma_f32_16x16x32_bf16 v[60:63], v[140:143], v[184:187], v[60:63]
	v_mfma_f32_16x16x32_bf16 v[60:63], v[156:159], v[188:191], v[60:63]
	v_mfma_f32_16x16x32_bf16 v[56:59], v[160:163], v[184:187], v[56:59]
	v_mfma_f32_16x16x32_bf16 v[56:59], v[164:167], v[188:191], v[56:59]
	v_mfma_f32_16x16x32_bf16 v[44:47], v[140:143], v[192:195], v[44:47]
	v_mfma_f32_16x16x32_bf16 v[44:47], v[156:159], v[196:199], v[44:47]
	v_mfma_f32_16x16x32_bf16 v[40:43], v[160:163], v[192:195], v[40:43]
	v_mfma_f32_16x16x32_bf16 v[40:43], v[164:167], v[196:199], v[40:43]
	v_mfma_f32_16x16x32_bf16 v[28:31], v[140:143], v[200:203], v[28:31]
	v_mfma_f32_16x16x32_bf16 v[28:31], v[156:159], v[204:207], v[28:31]
	v_mfma_f32_16x16x32_bf16 v[24:27], v[160:163], v[200:203], v[24:27]
	v_mfma_f32_16x16x32_bf16 v[24:27], v[164:167], v[204:207], v[24:27]
	v_mfma_f32_16x16x32_bf16 v[12:15], v[140:143], v[208:211], v[12:15]
	v_mfma_f32_16x16x32_bf16 v[12:15], v[156:159], v[212:215], v[12:15]
	v_mfma_f32_16x16x32_bf16 v[8:11], v[160:163], v[208:211], v[8:11]
	v_mfma_f32_16x16x32_bf16 v[8:11], v[164:167], v[212:215], v[8:11]
	s_setprio 0
	s_setprio 2
	v_mfma_f32_16x16x32_bf16 v[52:55], v[168:171], v[184:187], v[52:55]
	v_mfma_f32_16x16x32_bf16 v[52:55], v[172:175], v[188:191], v[52:55]
	v_mfma_f32_16x16x32_bf16 v[48:51], v[176:179], v[184:187], v[48:51]
	v_mfma_f32_16x16x32_bf16 v[48:51], v[180:183], v[188:191], v[48:51]
	v_mfma_f32_16x16x32_bf16 v[36:39], v[168:171], v[192:195], v[36:39]
	v_mfma_f32_16x16x32_bf16 v[36:39], v[172:175], v[196:199], v[36:39]
	v_mfma_f32_16x16x32_bf16 v[32:35], v[176:179], v[192:195], v[32:35]
	v_mfma_f32_16x16x32_bf16 v[32:35], v[180:183], v[196:199], v[32:35]
	v_mfma_f32_16x16x32_bf16 v[20:23], v[168:171], v[200:203], v[20:23]
	v_mfma_f32_16x16x32_bf16 v[20:23], v[172:175], v[204:207], v[20:23]
	v_mfma_f32_16x16x32_bf16 v[16:19], v[176:179], v[200:203], v[16:19]
	v_mfma_f32_16x16x32_bf16 v[16:19], v[180:183], v[204:207], v[16:19]
	v_mfma_f32_16x16x32_bf16 v[4:7], v[168:171], v[208:211], v[4:7]
	v_mfma_f32_16x16x32_bf16 v[4:7], v[172:175], v[212:215], v[4:7]
	s_setprio 3
	s_barrier
	v_mfma_f32_16x16x32_bf16 v[0:3], v[176:179], v[208:211], v[0:3]
	v_mfma_f32_16x16x32_bf16 v[0:3], v[180:183], v[212:215], v[0:3]
	s_setprio 0
	s_add_i32 s50, s50, 2
	s_add_u32 s14, s14, 0x100
	s_addc_u32 s15, s15, 0
	s_add_u32 s48, s48, 0x100
	s_addc_u32 s49, s49, 0
	s_cmpk_gt_u32 s50, 0xfd
	s_cbranch_scc0 .LBB0_350
	s_and_b64 vcc, exec, s[10:11]
	s_cbranch_vccz .LBB0_353
	s_barrier
